# M16: in-proj GEMM with v_mfma_f32_16x16x32_bf16 (same bf16 operands, f32 accumulate), accumulators converted to the 32x32 epilogue layout through one LDS round trip per tile
# baseline (speedup 1.0000x reference)
.LBB0_183:
	s_ashr_i32 s1, s0, 31
	s_lshl_b64 s[4:5], s[0:1], 18
	s_add_u32 s8, s48, s4
	s_addc_u32 s9, s49, s5
	s_ashr_i32 s45, s44, 31
	s_lshl_b64 s[6:7], s[44:45], 18
	v_mov_b32_e32 v38, v156
	s_add_u32 s10, s22, s6
	s_addc_u32 s11, s23, s7
	v_readfirstlane_b32 s12, v38
	s_ashr_i32 s1, s12, 6
	v_bfe_u32 v0, v38, 3, 3
	v_lshl_or_b32 v2, s1, 5, v0
	v_min_i32_e32 v4, 0x7f, v2
	v_or_b32_e32 v10, 8, v2
	v_or_b32_e32 v20, 16, v2
	v_or_b32_e32 v28, 24, v2
	v_ashrrev_i32_e32 v5, 31, v4
	v_lshrrev_b32_e32 v11, 1, v10
	v_min_i32_e32 v12, 0x7f, v10
	v_min_i32_e32 v22, 0x7f, v20
	v_min_i32_e32 v30, 0x7f, v28
	v_lshlrev_b64 v[4:5], 11, v[4:5]
	v_lshlrev_b32_e32 v0, 4, v38
	v_and_b32_e32 v40, 48, v38
	v_ashrrev_i32_e32 v3, 31, v2
	v_xor_b32_e32 v11, v11, v38
	v_ashrrev_i32_e32 v13, 31, v12
	v_ashrrev_i32_e32 v23, 31, v22
	v_ashrrev_i32_e32 v31, 31, v30
	v_lshl_add_u64 v[4:5], s[8:9], 0, v[4:5]
	v_and_b32_e32 v41, 0x70, v0
	v_bitop3_b32 v0, v0, v40, s19 bitop3:0x6c
	v_lshlrev_b64 v[6:7], 11, v[2:3]
	v_lshlrev_b64 v[12:13], 11, v[12:13]
	v_lshlrev_b32_e32 v11, 4, v11
	v_lshlrev_b64 v[22:23], 11, v[22:23]
	v_lshrrev_b32_e32 v29, 1, v28
	v_lshlrev_b64 v[30:31], 11, v[30:31]
	s_lshl_b32 s1, s1, 12
	v_lshl_add_u64 v[4:5], v[4:5], 0, v[0:1]
	v_lshl_add_u64 v[8:9], s[10:11], 0, v[6:7]
	v_lshl_add_u64 v[12:13], s[8:9], 0, v[12:13]
	v_and_b32_e32 v14, 0x70, v11
	v_ashrrev_i32_e32 v11, 31, v10
	v_lshl_add_u64 v[22:23], s[8:9], 0, v[22:23]
	v_xor_b32_e32 v29, v29, v38
	v_lshl_add_u64 v[30:31], s[8:9], 0, v[30:31]
	s_add_i32 s8, s1, 0x4000
	s_mov_b32 m0, s1
	v_lshl_add_u64 v[8:9], v[8:9], 0, v[0:1]
	v_mov_b32_e32 v15, v1
	v_lshlrev_b64 v[16:17], 11, v[10:11]
	v_lshlrev_b32_e32 v29, 4, v29
	s_barrier
	global_load_lds_dwordx4 v[4:5], off
	s_mov_b32 m0, s8
	v_lshl_add_u64 v[12:13], v[12:13], 0, v[14:15]
	v_lshl_add_u64 v[18:19], s[10:11], 0, v[16:17]
	v_ashrrev_i32_e32 v21, 31, v20
	v_and_b32_e32 v32, 0x70, v29
	v_ashrrev_i32_e32 v29, 31, v28
	global_load_lds_dwordx4 v[8:9], off
	s_or_b32 m0, s1, 0x400
	s_add_i32 s9, s1, 0x4400
	v_lshl_add_u64 v[18:19], v[18:19], 0, v[14:15]
	v_lshlrev_b64 v[24:25], 11, v[20:21]
	v_lshlrev_b64 v[34:35], 11, v[28:29]
	global_load_lds_dwordx4 v[12:13], off
	s_mov_b32 m0, s9
	v_lshl_add_u64 v[22:23], v[22:23], 0, v[0:1]
	v_lshl_add_u64 v[26:27], s[10:11], 0, v[24:25]
	v_lshl_add_u64 v[36:37], s[10:11], 0, v[34:35]
	global_load_lds_dwordx4 v[18:19], off
	s_or_b32 m0, s1, 0x800
	s_add_i32 s10, s1, 0x4800
	v_lshl_add_u64 v[26:27], v[26:27], 0, v[0:1]
	v_mov_b32_e32 v33, v1
	global_load_lds_dwordx4 v[22:23], off
	s_mov_b32 m0, s10
	v_lshl_add_u64 v[30:31], v[30:31], 0, v[32:33]
	global_load_lds_dwordx4 v[26:27], off
	s_or_b32 m0, s1, 0xc00
	s_add_i32 s11, s1, 0x4c00
	v_lshl_add_u64 v[36:37], v[36:37], 0, v[32:33]
	global_load_lds_dwordx4 v[30:31], off
	s_mov_b32 m0, s11
	s_lshr_b32 s13, s12, 1
	global_load_lds_dwordx4 v[36:37], off
	v_and_b32_e32 v39, 31, v38
	s_and_b32 s13, s13, 0x1ffffc0
	v_or_b32_e32 v9, s13, v39
	v_cmp_gt_i64_e32 vcc, s[30:31], v[2:3]
	s_mul_i32 s13, s2, 0x7c0000
	s_add_u32 s6, s13, s6
	v_cndmask_b32_e32 v3, 0, v3, vcc
	v_cndmask_b32_e32 v2, v164, v2, vcc
	s_mul_hi_u32 s13, s2, 0x7c0000
	v_lshlrev_b64 v[2:3], 11, v[2:3]
	s_addc_u32 s7, s13, s7
	v_lshl_add_u64 v[66:67], s[4:5], 0, v[2:3]
	v_lshl_add_u64 v[2:3], s[6:7], 0, v[6:7]
	v_cmp_gt_i64_e32 vcc, s[30:31], v[10:11]
	v_lshl_add_u64 v[68:69], v[2:3], 0, v[0:1]
	v_bfe_u32 v4, v38, 5, 1
	v_cndmask_b32_e32 v3, 0, v11, vcc
	v_cndmask_b32_e32 v2, v164, v10, vcc
	v_lshlrev_b64 v[2:3], 11, v[2:3]
	v_lshrrev_b32_e32 v5, 1, v38
	v_lshl_add_u64 v[70:71], s[4:5], 0, v[2:3]
	v_lshl_add_u64 v[2:3], s[6:7], 0, v[16:17]
	v_cmp_gt_i64_e32 vcc, s[30:31], v[20:21]
	v_and_or_b32 v12, s12, 64, v39
	v_bitop3_b32 v5, v4, v5, 7 bitop3:0x78
	v_lshl_add_u64 v[72:73], v[2:3], 0, v[14:15]
	v_cndmask_b32_e32 v3, 0, v21, vcc
	v_cndmask_b32_e32 v2, v164, v20, vcc
	v_bfe_u32 v8, v38, 1, 3
	v_lshlrev_b32_e32 v9, 7, v9
	v_lshl_or_b32 v12, v12, 7, v163
	v_lshlrev_b32_e32 v5, 4, v5
	v_lshlrev_b64 v[2:3], 11, v[2:3]
	v_or_b32_e32 v84, v9, v5
	v_or_b32_e32 v85, v12, v5
	v_bitop3_b32 v5, v4, v8, 2 bitop3:0x36
	v_lshl_add_u64 v[74:75], s[4:5], 0, v[2:3]
	v_lshl_add_u64 v[2:3], s[6:7], 0, v[24:25]
	v_cmp_gt_i64_e32 vcc, s[30:31], v[28:29]
	v_lshlrev_b32_e32 v5, 4, v5
	v_lshl_add_u64 v[76:77], v[2:3], 0, v[0:1]
	v_cndmask_b32_e32 v3, 0, v29, vcc
	v_cndmask_b32_e32 v2, v164, v28, vcc
	s_waitcnt vmcnt(0)
	v_or_b32_e32 v86, v9, v5
	v_or_b32_e32 v87, v12, v5
	v_bitop3_b32 v5, v4, v8, 4 bitop3:0x36
	v_bitop3_b32 v4, v4, v8, 6 bitop3:0x36
	v_lshlrev_b64 v[2:3], 11, v[2:3]
	v_lshlrev_b32_e32 v5, 4, v5
	v_lshlrev_b32_e32 v4, 4, v4
	v_lshl_add_u64 v[78:79], s[4:5], 0, v[2:3]
	v_lshl_add_u64 v[2:3], s[6:7], 0, v[34:35]
	v_mov_b32_e32 v34, 0
	v_or_b32_e32 v88, v9, v5
	v_or_b32_e32 v89, v12, v5
	v_or_b32_e32 v90, v9, v4
	v_or_b32_e32 v91, v12, v4
	s_mov_b32 s12, 0
	v_bitop3_b32 v66, v66, v41, v40 bitop3:0xf6
	v_or_b32_e32 v70, v70, v14
	v_bitop3_b32 v74, v74, v41, v40 bitop3:0xf6
	v_or_b32_e32 v78, v78, v32
	v_lshl_add_u64 v[80:81], v[2:3], 0, v[32:33]
	s_add_i32 s6, s1, 0x8000
	s_add_i32 s7, s1, 0xc000
	s_add_i32 s13, s1, 0x8400
	s_add_i32 s14, s1, 0xc400
	s_add_i32 s15, s1, 0x8800
	s_add_i32 s16, s1, 0xc800
	s_add_i32 s17, s1, 0x8c00
	s_add_i32 s25, s1, 0xcc00
	v_mov_b32_e32 v35, v34
	v_mov_b32_e32 v36, v34
	v_mov_b32_e32 v37, v34
	v_mov_b32_e32 v38, v34
	v_mov_b32_e32 v39, v34
	v_mov_b32_e32 v40, v34
	v_mov_b32_e32 v41, v34
	v_mov_b32_e32 v42, v34
	v_mov_b32_e32 v43, v34
	v_mov_b32_e32 v44, v34
	v_mov_b32_e32 v45, v34
	v_mov_b32_e32 v46, v34
	v_mov_b32_e32 v47, v34
	v_mov_b32_e32 v48, v34
	v_mov_b32_e32 v49, v34
	v_mov_b32_e32 v2, v34
	v_mov_b32_e32 v3, v34
	v_mov_b32_e32 v4, v34
	v_mov_b32_e32 v5, v34
	v_mov_b32_e32 v6, v34
	v_mov_b32_e32 v7, v34
	v_mov_b32_e32 v8, v34
	v_mov_b32_e32 v9, v34
	v_mov_b32_e32 v10, v34
	v_mov_b32_e32 v11, v34
	v_mov_b32_e32 v12, v34
	v_mov_b32_e32 v13, v34
	v_mov_b32_e32 v14, v34
	v_mov_b32_e32 v15, v34
	v_mov_b32_e32 v16, v34
	v_mov_b32_e32 v17, v34
	v_mov_b32_e32 v50, v34
	v_mov_b32_e32 v51, v34
	v_mov_b32_e32 v52, v34
	v_mov_b32_e32 v53, v34
	v_mov_b32_e32 v54, v34
	v_mov_b32_e32 v55, v34
	v_mov_b32_e32 v56, v34
	v_mov_b32_e32 v57, v34
	v_mov_b32_e32 v58, v34
	v_mov_b32_e32 v59, v34
	v_mov_b32_e32 v60, v34
	v_mov_b32_e32 v61, v34
	v_mov_b32_e32 v62, v34
	v_mov_b32_e32 v63, v34
	v_mov_b32_e32 v64, v34
	v_mov_b32_e32 v65, v34
	v_mov_b32_e32 v18, v34
	v_mov_b32_e32 v19, v34
	v_mov_b32_e32 v20, v34
	v_mov_b32_e32 v21, v34
	v_mov_b32_e32 v22, v34
	v_mov_b32_e32 v23, v34
	v_mov_b32_e32 v24, v34
	v_mov_b32_e32 v25, v34
	v_mov_b32_e32 v26, v34
	v_mov_b32_e32 v27, v34
	v_mov_b32_e32 v28, v34
	v_mov_b32_e32 v29, v34
	v_mov_b32_e32 v30, v34
	v_mov_b32_e32 v31, v34
	v_mov_b32_e32 v32, v34
	v_mov_b32_e32 v33, v34
	s_waitcnt vmcnt(0) lgkmcnt(0)
	s_barrier
	v_lshl_add_u64 v[66:67], s[80:81], 0, v[66:67]
	v_lshl_add_u64 v[66:67], v[66:67], 0, s[64:65]
	v_lshl_add_u64 v[68:69], s[80:81], 0, v[68:69]
	v_lshl_add_u64 v[68:69], v[68:69], 0, s[66:67]
	v_lshl_add_u64 v[70:71], s[80:81], 0, v[70:71]
	v_lshl_add_u64 v[70:71], v[70:71], 0, s[64:65]
	v_lshl_add_u64 v[72:73], s[80:81], 0, v[72:73]
	v_lshl_add_u64 v[72:73], v[72:73], 0, s[66:67]
	v_lshl_add_u64 v[74:75], s[80:81], 0, v[74:75]
	v_lshl_add_u64 v[74:75], v[74:75], 0, s[64:65]
	v_lshl_add_u64 v[76:77], s[80:81], 0, v[76:77]
	v_lshl_add_u64 v[76:77], v[76:77], 0, s[66:67]
	v_lshl_add_u64 v[78:79], s[80:81], 0, v[78:79]
	v_lshl_add_u64 v[78:79], v[78:79], 0, s[64:65]
	v_lshl_add_u64 v[80:81], s[80:81], 0, v[80:81]
	v_lshl_add_u64 v[80:81], v[80:81], 0, s[66:67]
	v_and_b32_e32 v88, 63, v156
	v_and_b32_e32 v89, 15, v88
	v_bfe_u32 v90, v88, 1, 3
	v_lshrrev_b32_e32 v91, 4, v88
	v_xor_b32_e32 v90, v91, v90
	v_lshlrev_b32_e32 v90, 4, v90
	s_lshr_b32 s72, s1, 12
	s_lshr_b32 s73, s72, 1
	s_and_b32 s72, s72, 1
	s_lshl_b32 s73, s73, 13
	s_lshl_b32 s72, s72, 13
	s_add_u32 s72, s72, 0x4000
	v_lshl_add_u32 v84, v89, 7, v90
	v_add_u32_e32 v85, s72, v84
	v_add_u32_e32 v84, s73, v84
	v_xor_b32_e32 v86, 64, v84
	v_xor_b32_e32 v87, 64, v85
	s_mov_b64 s[26:27], 0x40000
	s_mov_b64 s[72:73], 0x3ff80
	s_mov_b32 m0, s6
	v_lshl_add_u64 v[82:83], v[66:67], 0, s[72:73]
	s_nop 0
	global_load_lds_dwordx4 v[82:83], off
	s_mov_b32 m0, s13
	v_lshl_add_u64 v[82:83], v[70:71], 0, s[72:73]
	s_nop 0
	global_load_lds_dwordx4 v[82:83], off
	s_mov_b32 m0, s15
	v_lshl_add_u64 v[82:83], v[74:75], 0, s[72:73]
	s_nop 0
	global_load_lds_dwordx4 v[82:83], off
	s_mov_b32 m0, s17
	v_lshl_add_u64 v[82:83], v[78:79], 0, s[72:73]
	s_nop 0
	global_load_lds_dwordx4 v[82:83], off
	s_mov_b32 m0, s7
	s_nop 0
	global_load_lds_dwordx4 v[68:69], off
	v_lshl_add_u64 v[68:69], v[68:69], 0, s[34:35]
	s_mov_b32 m0, s14
	s_nop 0
	global_load_lds_dwordx4 v[72:73], off
	v_lshl_add_u64 v[72:73], v[72:73], 0, s[34:35]
	s_mov_b32 m0, s16
	s_nop 0
	global_load_lds_dwordx4 v[76:77], off
	v_lshl_add_u64 v[76:77], v[76:77], 0, s[34:35]
	s_mov_b32 m0, s25
	s_nop 0
	global_load_lds_dwordx4 v[80:81], off
	v_lshl_add_u64 v[80:81], v[80:81], 0, s[34:35]
	v_mov_b32_e32 v104, 0
	v_mov_b32_e32 v105, 0
	v_mov_b32_e32 v106, 0
	v_mov_b32_e32 v107, 0
	v_mov_b32_e32 v108, 0
	v_mov_b32_e32 v109, 0
	v_mov_b32_e32 v110, 0
	v_mov_b32_e32 v111, 0
	v_mov_b32_e32 v112, 0
	v_mov_b32_e32 v113, 0
	v_mov_b32_e32 v114, 0
	v_mov_b32_e32 v115, 0
	v_mov_b32_e32 v116, 0
	v_mov_b32_e32 v117, 0
	v_mov_b32_e32 v118, 0
	v_mov_b32_e32 v119, 0
	v_mov_b32_e32 v128, 0
	v_mov_b32_e32 v129, 0
	v_mov_b32_e32 v130, 0
	v_mov_b32_e32 v131, 0
	v_mov_b32_e32 v132, 0
	v_mov_b32_e32 v133, 0
	v_mov_b32_e32 v134, 0
	v_mov_b32_e32 v135, 0
	v_mov_b32_e32 v136, 0
	v_mov_b32_e32 v137, 0
	v_mov_b32_e32 v138, 0
	v_mov_b32_e32 v139, 0
	v_mov_b32_e32 v140, 0
	v_mov_b32_e32 v141, 0
	v_mov_b32_e32 v142, 0
	v_mov_b32_e32 v143, 0
	v_mov_b32_e32 v196, 0
	v_mov_b32_e32 v197, 0
	v_mov_b32_e32 v198, 0
	v_mov_b32_e32 v199, 0
	v_mov_b32_e32 v200, 0
	v_mov_b32_e32 v201, 0
	v_mov_b32_e32 v202, 0
	v_mov_b32_e32 v203, 0
	v_mov_b32_e32 v204, 0
	v_mov_b32_e32 v205, 0
	v_mov_b32_e32 v206, 0
	v_mov_b32_e32 v207, 0
	v_mov_b32_e32 v208, 0
	v_mov_b32_e32 v209, 0
	v_mov_b32_e32 v210, 0
	v_mov_b32_e32 v211, 0
	v_mov_b32_e32 v236, 0
	v_mov_b32_e32 v237, 0
	v_mov_b32_e32 v238, 0
	v_mov_b32_e32 v239, 0
	v_mov_b32_e32 v240, 0
	v_mov_b32_e32 v241, 0
	v_mov_b32_e32 v242, 0
	v_mov_b32_e32 v243, 0
	v_mov_b32_e32 v244, 0
	v_mov_b32_e32 v245, 0
	v_mov_b32_e32 v246, 0
	v_mov_b32_e32 v247, 0
	v_mov_b32_e32 v248, 0
	v_mov_b32_e32 v249, 0
	v_mov_b32_e32 v250, 0
	v_mov_b32_e32 v251, 0
	s_mov_b32 s12, 0
	s_lshr_b32 s72, s1, 12
	s_cmp_eq_u32 s72, 1
	s_cbranch_scc1 .Lg1_loop_w1
	s_cmp_eq_u32 s72, 2
	s_cbranch_scc1 .Lg1_loop_w2
	s_cmp_eq_u32 s72, 3
	s_cbranch_scc1 .Lg1_loop_w3
.Lg1_loop:
	ds_read_b128 v[92:95], v84 offset:0
	ds_read_b128 v[100:103], v84 offset:2048
	ds_read_b128 v[148:151], v84 offset:4096
	ds_read_b128 v[180:183], v84 offset:6144
	ds_read_b128 v[188:191], v85 offset:0
	ds_read_b128 v[212:215], v85 offset:2048
	ds_read_b128 v[220:223], v85 offset:4096
	ds_read_b128 v[228:231], v85 offset:6144
	ds_read_b128 v[96:99], v86 offset:0
	ds_read_b128 v[144:147], v86 offset:2048
	ds_read_b128 v[152:155], v86 offset:4096
	ds_read_b128 v[184:187], v86 offset:6144
	ds_read_b128 v[192:195], v87 offset:0
	ds_read_b128 v[216:219], v87 offset:2048
	ds_read_b128 v[224:227], v87 offset:4096
	ds_read_b128 v[252:255], v87 offset:6144
	s_waitcnt lgkmcnt(0)
	s_barrier
	s_mov_b32 m0, s1
	v_mfma_f32_16x16x32_bf16 v[2:5], v[92:95], v[188:191], v[2:5]
	global_load_lds_dwordx4 v[66:67], off
	v_mfma_f32_16x16x32_bf16 v[6:9], v[92:95], v[212:215], v[6:9]
	v_mfma_f32_16x16x32_bf16 v[10:13], v[92:95], v[220:223], v[10:13]
	v_mfma_f32_16x16x32_bf16 v[14:17], v[92:95], v[228:231], v[14:17]
	v_mfma_f32_16x16x32_bf16 v[18:21], v[100:103], v[188:191], v[18:21]
	v_mfma_f32_16x16x32_bf16 v[22:25], v[100:103], v[212:215], v[22:25]
	s_add_i32 m0, s1, 0x400
	v_mfma_f32_16x16x32_bf16 v[26:29], v[100:103], v[220:223], v[26:29]
	global_load_lds_dwordx4 v[70:71], off
	v_mfma_f32_16x16x32_bf16 v[30:33], v[100:103], v[228:231], v[30:33]
	v_mfma_f32_16x16x32_bf16 v[34:37], v[148:151], v[188:191], v[34:37]
	v_mfma_f32_16x16x32_bf16 v[38:41], v[148:151], v[212:215], v[38:41]
	s_add_i32 m0, s1, 0x800
	v_mfma_f32_16x16x32_bf16 v[42:45], v[148:151], v[220:223], v[42:45]
	global_load_lds_dwordx4 v[74:75], off
	v_mfma_f32_16x16x32_bf16 v[46:49], v[148:151], v[228:231], v[46:49]
	v_mfma_f32_16x16x32_bf16 v[50:53], v[180:183], v[188:191], v[50:53]
	v_mfma_f32_16x16x32_bf16 v[54:57], v[180:183], v[212:215], v[54:57]
	v_mfma_f32_16x16x32_bf16 v[58:61], v[180:183], v[220:223], v[58:61]
	v_mfma_f32_16x16x32_bf16 v[62:65], v[180:183], v[228:231], v[62:65]
	s_add_i32 m0, s1, 0xc00
	v_mfma_f32_16x16x32_bf16 v[2:5], v[96:99], v[192:195], v[2:5]
	global_load_lds_dwordx4 v[78:79], off
	v_mfma_f32_16x16x32_bf16 v[6:9], v[96:99], v[216:219], v[6:9]
	v_mfma_f32_16x16x32_bf16 v[10:13], v[96:99], v[224:227], v[10:13]
	v_mfma_f32_16x16x32_bf16 v[14:17], v[96:99], v[252:255], v[14:17]
	v_mfma_f32_16x16x32_bf16 v[18:21], v[144:147], v[192:195], v[18:21]
	v_mfma_f32_16x16x32_bf16 v[22:25], v[144:147], v[216:219], v[22:25]
	s_mov_b32 m0, s8
	v_mfma_f32_16x16x32_bf16 v[26:29], v[144:147], v[224:227], v[26:29]
	global_load_lds_dwordx4 v[68:69], off
	v_lshl_add_u64 v[68:69], v[68:69], 0, s[34:35]
	v_mfma_f32_16x16x32_bf16 v[30:33], v[144:147], v[252:255], v[30:33]
	v_mfma_f32_16x16x32_bf16 v[34:37], v[152:155], v[192:195], v[34:37]
	v_mfma_f32_16x16x32_bf16 v[38:41], v[152:155], v[216:219], v[38:41]
	s_mov_b32 m0, s9
	v_mfma_f32_16x16x32_bf16 v[42:45], v[152:155], v[224:227], v[42:45]
	global_load_lds_dwordx4 v[72:73], off
	v_lshl_add_u64 v[72:73], v[72:73], 0, s[34:35]
	v_mfma_f32_16x16x32_bf16 v[46:49], v[152:155], v[252:255], v[46:49]
	v_mfma_f32_16x16x32_bf16 v[50:53], v[184:187], v[192:195], v[50:53]
	v_mfma_f32_16x16x32_bf16 v[54:57], v[184:187], v[216:219], v[54:57]
	v_mfma_f32_16x16x32_bf16 v[58:61], v[184:187], v[224:227], v[58:61]
	v_mfma_f32_16x16x32_bf16 v[62:65], v[184:187], v[252:255], v[62:65]
	s_waitcnt vmcnt(6)
	s_barrier
	ds_read_b128 v[92:95], v84 offset:32768
	ds_read_b128 v[100:103], v84 offset:34816
	ds_read_b128 v[148:151], v84 offset:36864
	ds_read_b128 v[180:183], v84 offset:38912
	ds_read_b128 v[96:99], v86 offset:32768
	ds_read_b128 v[144:147], v86 offset:34816
	ds_read_b128 v[152:155], v86 offset:36864
	ds_read_b128 v[184:187], v86 offset:38912
	s_waitcnt lgkmcnt(0)
	s_barrier
	s_mov_b32 m0, s6
	v_lshl_add_u64 v[82:83], v[66:67], 0, s[26:27]
	v_mfma_f32_16x16x32_bf16 v[104:107], v[92:95], v[188:191], v[104:107]
	global_load_lds_dwordx4 v[82:83], off
	v_lshl_add_u64 v[66:67], v[66:67], 0, s[34:35]
	v_mfma_f32_16x16x32_bf16 v[108:111], v[92:95], v[212:215], v[108:111]
	v_mfma_f32_16x16x32_bf16 v[112:115], v[92:95], v[220:223], v[112:115]
	v_mfma_f32_16x16x32_bf16 v[116:119], v[92:95], v[228:231], v[116:119]
	v_mfma_f32_16x16x32_bf16 v[128:131], v[100:103], v[188:191], v[128:131]
	v_mfma_f32_16x16x32_bf16 v[132:135], v[100:103], v[212:215], v[132:135]
	s_mov_b32 m0, s13
	v_lshl_add_u64 v[82:83], v[70:71], 0, s[26:27]
	v_mfma_f32_16x16x32_bf16 v[136:139], v[100:103], v[220:223], v[136:139]
	global_load_lds_dwordx4 v[82:83], off
	v_lshl_add_u64 v[70:71], v[70:71], 0, s[34:35]
	v_mfma_f32_16x16x32_bf16 v[140:143], v[100:103], v[228:231], v[140:143]
	v_mfma_f32_16x16x32_bf16 v[196:199], v[148:151], v[188:191], v[196:199]
	v_mfma_f32_16x16x32_bf16 v[200:203], v[148:151], v[212:215], v[200:203]
	s_mov_b32 m0, s15
	v_lshl_add_u64 v[82:83], v[74:75], 0, s[26:27]
	v_mfma_f32_16x16x32_bf16 v[204:207], v[148:151], v[220:223], v[204:207]
	global_load_lds_dwordx4 v[82:83], off
	v_lshl_add_u64 v[74:75], v[74:75], 0, s[34:35]
	v_mfma_f32_16x16x32_bf16 v[208:211], v[148:151], v[228:231], v[208:211]
	v_mfma_f32_16x16x32_bf16 v[236:239], v[180:183], v[188:191], v[236:239]
	v_mfma_f32_16x16x32_bf16 v[240:243], v[180:183], v[212:215], v[240:243]
	v_mfma_f32_16x16x32_bf16 v[244:247], v[180:183], v[220:223], v[244:247]
	v_mfma_f32_16x16x32_bf16 v[248:251], v[180:183], v[228:231], v[248:251]
	s_mov_b32 m0, s17
	v_lshl_add_u64 v[82:83], v[78:79], 0, s[26:27]
	v_mfma_f32_16x16x32_bf16 v[104:107], v[96:99], v[192:195], v[104:107]
	global_load_lds_dwordx4 v[82:83], off
	v_lshl_add_u64 v[78:79], v[78:79], 0, s[34:35]
	v_mfma_f32_16x16x32_bf16 v[108:111], v[96:99], v[216:219], v[108:111]
	v_mfma_f32_16x16x32_bf16 v[112:115], v[96:99], v[224:227], v[112:115]
	v_mfma_f32_16x16x32_bf16 v[116:119], v[96:99], v[252:255], v[116:119]
	v_mfma_f32_16x16x32_bf16 v[128:131], v[144:147], v[192:195], v[128:131]
	v_mfma_f32_16x16x32_bf16 v[132:135], v[144:147], v[216:219], v[132:135]
	s_mov_b32 m0, s10
	v_mfma_f32_16x16x32_bf16 v[136:139], v[144:147], v[224:227], v[136:139]
	global_load_lds_dwordx4 v[76:77], off
	v_lshl_add_u64 v[76:77], v[76:77], 0, s[34:35]
	v_mfma_f32_16x16x32_bf16 v[140:143], v[144:147], v[252:255], v[140:143]
	v_mfma_f32_16x16x32_bf16 v[196:199], v[152:155], v[192:195], v[196:199]
	v_mfma_f32_16x16x32_bf16 v[200:203], v[152:155], v[216:219], v[200:203]
	s_mov_b32 m0, s11
	v_mfma_f32_16x16x32_bf16 v[204:207], v[152:155], v[224:227], v[204:207]
	global_load_lds_dwordx4 v[80:81], off
	v_lshl_add_u64 v[80:81], v[80:81], 0, s[34:35]
	v_mfma_f32_16x16x32_bf16 v[208:211], v[152:155], v[252:255], v[208:211]
	v_mfma_f32_16x16x32_bf16 v[236:239], v[184:187], v[192:195], v[236:239]
	v_mfma_f32_16x16x32_bf16 v[240:243], v[184:187], v[216:219], v[240:243]
	v_mfma_f32_16x16x32_bf16 v[244:247], v[184:187], v[224:227], v[244:247]
	v_mfma_f32_16x16x32_bf16 v[248:251], v[184:187], v[252:255], v[248:251]
	s_waitcnt vmcnt(6)
	s_barrier
	ds_read_b128 v[92:95], v84 offset:0
	ds_read_b128 v[100:103], v84 offset:2048
	ds_read_b128 v[148:151], v84 offset:4096
	ds_read_b128 v[180:183], v84 offset:6144
	ds_read_b128 v[188:191], v85 offset:32768
	ds_read_b128 v[212:215], v85 offset:34816
	ds_read_b128 v[220:223], v85 offset:36864
	ds_read_b128 v[228:231], v85 offset:38912
	ds_read_b128 v[96:99], v86 offset:0
	ds_read_b128 v[144:147], v86 offset:2048
	ds_read_b128 v[152:155], v86 offset:4096
	ds_read_b128 v[184:187], v86 offset:6144
	ds_read_b128 v[192:195], v87 offset:32768
	ds_read_b128 v[216:219], v87 offset:34816
	ds_read_b128 v[224:227], v87 offset:36864
	ds_read_b128 v[252:255], v87 offset:38912
	s_waitcnt lgkmcnt(0)
	s_barrier
	s_mov_b32 m0, s1
	v_mfma_f32_16x16x32_bf16 v[2:5], v[92:95], v[188:191], v[2:5]
	global_load_lds_dwordx4 v[66:67], off
	v_mfma_f32_16x16x32_bf16 v[6:9], v[92:95], v[212:215], v[6:9]
	v_mfma_f32_16x16x32_bf16 v[10:13], v[92:95], v[220:223], v[10:13]
	v_mfma_f32_16x16x32_bf16 v[14:17], v[92:95], v[228:231], v[14:17]
	v_mfma_f32_16x16x32_bf16 v[18:21], v[100:103], v[188:191], v[18:21]
	v_mfma_f32_16x16x32_bf16 v[22:25], v[100:103], v[212:215], v[22:25]
	s_add_i32 m0, s1, 0x400
	v_mfma_f32_16x16x32_bf16 v[26:29], v[100:103], v[220:223], v[26:29]
	global_load_lds_dwordx4 v[70:71], off
	v_mfma_f32_16x16x32_bf16 v[30:33], v[100:103], v[228:231], v[30:33]
	v_mfma_f32_16x16x32_bf16 v[34:37], v[148:151], v[188:191], v[34:37]
	v_mfma_f32_16x16x32_bf16 v[38:41], v[148:151], v[212:215], v[38:41]
	s_add_i32 m0, s1, 0x800
	v_mfma_f32_16x16x32_bf16 v[42:45], v[148:151], v[220:223], v[42:45]
	global_load_lds_dwordx4 v[74:75], off
	v_mfma_f32_16x16x32_bf16 v[46:49], v[148:151], v[228:231], v[46:49]
	v_mfma_f32_16x16x32_bf16 v[50:53], v[180:183], v[188:191], v[50:53]
	v_mfma_f32_16x16x32_bf16 v[54:57], v[180:183], v[212:215], v[54:57]
	v_mfma_f32_16x16x32_bf16 v[58:61], v[180:183], v[220:223], v[58:61]
	v_mfma_f32_16x16x32_bf16 v[62:65], v[180:183], v[228:231], v[62:65]
	s_add_i32 m0, s1, 0xc00
	v_mfma_f32_16x16x32_bf16 v[2:5], v[96:99], v[192:195], v[2:5]
	global_load_lds_dwordx4 v[78:79], off
	v_mfma_f32_16x16x32_bf16 v[6:9], v[96:99], v[216:219], v[6:9]
	v_mfma_f32_16x16x32_bf16 v[10:13], v[96:99], v[224:227], v[10:13]
	v_mfma_f32_16x16x32_bf16 v[14:17], v[96:99], v[252:255], v[14:17]
	v_mfma_f32_16x16x32_bf16 v[18:21], v[144:147], v[192:195], v[18:21]
	v_mfma_f32_16x16x32_bf16 v[22:25], v[144:147], v[216:219], v[22:25]
	s_mov_b32 m0, s7
	v_mfma_f32_16x16x32_bf16 v[26:29], v[144:147], v[224:227], v[26:29]
	global_load_lds_dwordx4 v[68:69], off
	v_lshl_add_u64 v[68:69], v[68:69], 0, s[34:35]
	v_mfma_f32_16x16x32_bf16 v[30:33], v[144:147], v[252:255], v[30:33]
	v_mfma_f32_16x16x32_bf16 v[34:37], v[152:155], v[192:195], v[34:37]
	v_mfma_f32_16x16x32_bf16 v[38:41], v[152:155], v[216:219], v[38:41]
	s_mov_b32 m0, s14
	v_mfma_f32_16x16x32_bf16 v[42:45], v[152:155], v[224:227], v[42:45]
	global_load_lds_dwordx4 v[72:73], off
	v_lshl_add_u64 v[72:73], v[72:73], 0, s[34:35]
	v_mfma_f32_16x16x32_bf16 v[46:49], v[152:155], v[252:255], v[46:49]
	v_mfma_f32_16x16x32_bf16 v[50:53], v[184:187], v[192:195], v[50:53]
	v_mfma_f32_16x16x32_bf16 v[54:57], v[184:187], v[216:219], v[54:57]
	v_mfma_f32_16x16x32_bf16 v[58:61], v[184:187], v[224:227], v[58:61]
	v_mfma_f32_16x16x32_bf16 v[62:65], v[184:187], v[252:255], v[62:65]
	s_waitcnt vmcnt(6)
	s_barrier
	ds_read_b128 v[92:95], v84 offset:32768
	ds_read_b128 v[100:103], v84 offset:34816
	ds_read_b128 v[148:151], v84 offset:36864
	ds_read_b128 v[180:183], v84 offset:38912
	ds_read_b128 v[96:99], v86 offset:32768
	ds_read_b128 v[144:147], v86 offset:34816
	ds_read_b128 v[152:155], v86 offset:36864
	ds_read_b128 v[184:187], v86 offset:38912
	s_waitcnt lgkmcnt(0)
	s_barrier
	s_mov_b32 m0, s6
	v_lshl_add_u64 v[82:83], v[66:67], 0, s[26:27]
	v_mfma_f32_16x16x32_bf16 v[104:107], v[92:95], v[188:191], v[104:107]
	global_load_lds_dwordx4 v[82:83], off
	v_lshl_add_u64 v[66:67], v[66:67], 0, s[34:35]
	v_mfma_f32_16x16x32_bf16 v[108:111], v[92:95], v[212:215], v[108:111]
	v_mfma_f32_16x16x32_bf16 v[112:115], v[92:95], v[220:223], v[112:115]
	v_mfma_f32_16x16x32_bf16 v[116:119], v[92:95], v[228:231], v[116:119]
	v_mfma_f32_16x16x32_bf16 v[128:131], v[100:103], v[188:191], v[128:131]
	v_mfma_f32_16x16x32_bf16 v[132:135], v[100:103], v[212:215], v[132:135]
	s_mov_b32 m0, s13
	v_lshl_add_u64 v[82:83], v[70:71], 0, s[26:27]
	v_mfma_f32_16x16x32_bf16 v[136:139], v[100:103], v[220:223], v[136:139]
	global_load_lds_dwordx4 v[82:83], off
	v_lshl_add_u64 v[70:71], v[70:71], 0, s[34:35]
	v_mfma_f32_16x16x32_bf16 v[140:143], v[100:103], v[228:231], v[140:143]
	v_mfma_f32_16x16x32_bf16 v[196:199], v[148:151], v[188:191], v[196:199]
	v_mfma_f32_16x16x32_bf16 v[200:203], v[148:151], v[212:215], v[200:203]
	s_mov_b32 m0, s15
	v_lshl_add_u64 v[82:83], v[74:75], 0, s[26:27]
	v_mfma_f32_16x16x32_bf16 v[204:207], v[148:151], v[220:223], v[204:207]
	global_load_lds_dwordx4 v[82:83], off
	v_lshl_add_u64 v[74:75], v[74:75], 0, s[34:35]
	v_mfma_f32_16x16x32_bf16 v[208:211], v[148:151], v[228:231], v[208:211]
	v_mfma_f32_16x16x32_bf16 v[236:239], v[180:183], v[188:191], v[236:239]
	v_mfma_f32_16x16x32_bf16 v[240:243], v[180:183], v[212:215], v[240:243]
	v_mfma_f32_16x16x32_bf16 v[244:247], v[180:183], v[220:223], v[244:247]
	v_mfma_f32_16x16x32_bf16 v[248:251], v[180:183], v[228:231], v[248:251]
	s_mov_b32 m0, s17
	v_lshl_add_u64 v[82:83], v[78:79], 0, s[26:27]
	v_mfma_f32_16x16x32_bf16 v[104:107], v[96:99], v[192:195], v[104:107]
	global_load_lds_dwordx4 v[82:83], off
	v_lshl_add_u64 v[78:79], v[78:79], 0, s[34:35]
	v_mfma_f32_16x16x32_bf16 v[108:111], v[96:99], v[216:219], v[108:111]
	v_mfma_f32_16x16x32_bf16 v[112:115], v[96:99], v[224:227], v[112:115]
	v_mfma_f32_16x16x32_bf16 v[116:119], v[96:99], v[252:255], v[116:119]
	v_mfma_f32_16x16x32_bf16 v[128:131], v[144:147], v[192:195], v[128:131]
	v_mfma_f32_16x16x32_bf16 v[132:135], v[144:147], v[216:219], v[132:135]
	s_mov_b32 m0, s16
	v_mfma_f32_16x16x32_bf16 v[136:139], v[144:147], v[224:227], v[136:139]
	global_load_lds_dwordx4 v[76:77], off
	v_lshl_add_u64 v[76:77], v[76:77], 0, s[34:35]
	v_mfma_f32_16x16x32_bf16 v[140:143], v[144:147], v[252:255], v[140:143]
	v_mfma_f32_16x16x32_bf16 v[196:199], v[152:155], v[192:195], v[196:199]
	v_mfma_f32_16x16x32_bf16 v[200:203], v[152:155], v[216:219], v[200:203]
	s_mov_b32 m0, s25
	v_mfma_f32_16x16x32_bf16 v[204:207], v[152:155], v[224:227], v[204:207]
	global_load_lds_dwordx4 v[80:81], off
	v_lshl_add_u64 v[80:81], v[80:81], 0, s[34:35]
	v_mfma_f32_16x16x32_bf16 v[208:211], v[152:155], v[252:255], v[208:211]
	v_mfma_f32_16x16x32_bf16 v[236:239], v[184:187], v[192:195], v[236:239]
	v_mfma_f32_16x16x32_bf16 v[240:243], v[184:187], v[216:219], v[240:243]
	v_mfma_f32_16x16x32_bf16 v[244:247], v[184:187], v[224:227], v[244:247]
	v_mfma_f32_16x16x32_bf16 v[248:251], v[184:187], v[252:255], v[248:251]
	s_waitcnt vmcnt(6)
	s_barrier
	s_add_i32 s12, s12, 2
	s_cmp_lt_u32 s12, 14
	s_cbranch_scc1 .Lg1_loop
	ds_read_b128 v[92:95], v84 offset:0
	ds_read_b128 v[100:103], v84 offset:2048
	ds_read_b128 v[148:151], v84 offset:4096
	ds_read_b128 v[180:183], v84 offset:6144
	ds_read_b128 v[188:191], v85 offset:0
	ds_read_b128 v[212:215], v85 offset:2048
	ds_read_b128 v[220:223], v85 offset:4096
	ds_read_b128 v[228:231], v85 offset:6144
	ds_read_b128 v[96:99], v86 offset:0
	ds_read_b128 v[144:147], v86 offset:2048
	ds_read_b128 v[152:155], v86 offset:4096
	ds_read_b128 v[184:187], v86 offset:6144
	ds_read_b128 v[192:195], v87 offset:0
	ds_read_b128 v[216:219], v87 offset:2048
	ds_read_b128 v[224:227], v87 offset:4096
	ds_read_b128 v[252:255], v87 offset:6144
	s_waitcnt lgkmcnt(0)
	s_barrier
	s_mov_b32 m0, s1
	v_mfma_f32_16x16x32_bf16 v[2:5], v[92:95], v[188:191], v[2:5]
	global_load_lds_dwordx4 v[66:67], off
	v_mfma_f32_16x16x32_bf16 v[6:9], v[92:95], v[212:215], v[6:9]
	v_mfma_f32_16x16x32_bf16 v[10:13], v[92:95], v[220:223], v[10:13]
	v_mfma_f32_16x16x32_bf16 v[14:17], v[92:95], v[228:231], v[14:17]
	v_mfma_f32_16x16x32_bf16 v[18:21], v[100:103], v[188:191], v[18:21]
	v_mfma_f32_16x16x32_bf16 v[22:25], v[100:103], v[212:215], v[22:25]
	s_add_i32 m0, s1, 0x400
	v_mfma_f32_16x16x32_bf16 v[26:29], v[100:103], v[220:223], v[26:29]
	global_load_lds_dwordx4 v[70:71], off
	v_mfma_f32_16x16x32_bf16 v[30:33], v[100:103], v[228:231], v[30:33]
	v_mfma_f32_16x16x32_bf16 v[34:37], v[148:151], v[188:191], v[34:37]
	v_mfma_f32_16x16x32_bf16 v[38:41], v[148:151], v[212:215], v[38:41]
	v_mfma_f32_16x16x32_bf16 v[42:45], v[148:151], v[220:223], v[42:45]
	v_mfma_f32_16x16x32_bf16 v[46:49], v[148:151], v[228:231], v[46:49]
	v_mfma_f32_16x16x32_bf16 v[50:53], v[180:183], v[188:191], v[50:53]
	v_mfma_f32_16x16x32_bf16 v[54:57], v[180:183], v[212:215], v[54:57]
	v_mfma_f32_16x16x32_bf16 v[58:61], v[180:183], v[220:223], v[58:61]
	v_mfma_f32_16x16x32_bf16 v[62:65], v[180:183], v[228:231], v[62:65]
	s_add_i32 m0, s1, 0x800
	v_mfma_f32_16x16x32_bf16 v[2:5], v[96:99], v[192:195], v[2:5]
	global_load_lds_dwordx4 v[74:75], off
	v_mfma_f32_16x16x32_bf16 v[6:9], v[96:99], v[216:219], v[6:9]
	v_mfma_f32_16x16x32_bf16 v[10:13], v[96:99], v[224:227], v[10:13]
	v_mfma_f32_16x16x32_bf16 v[14:17], v[96:99], v[252:255], v[14:17]
	v_mfma_f32_16x16x32_bf16 v[18:21], v[144:147], v[192:195], v[18:21]
	v_mfma_f32_16x16x32_bf16 v[22:25], v[144:147], v[216:219], v[22:25]
	s_add_i32 m0, s1, 0xc00
	v_mfma_f32_16x16x32_bf16 v[26:29], v[144:147], v[224:227], v[26:29]
	global_load_lds_dwordx4 v[78:79], off
	v_mfma_f32_16x16x32_bf16 v[30:33], v[144:147], v[252:255], v[30:33]
	v_mfma_f32_16x16x32_bf16 v[34:37], v[152:155], v[192:195], v[34:37]
	v_mfma_f32_16x16x32_bf16 v[38:41], v[152:155], v[216:219], v[38:41]
	v_mfma_f32_16x16x32_bf16 v[42:45], v[152:155], v[224:227], v[42:45]
	v_mfma_f32_16x16x32_bf16 v[46:49], v[152:155], v[252:255], v[46:49]
	v_mfma_f32_16x16x32_bf16 v[50:53], v[184:187], v[192:195], v[50:53]
	v_mfma_f32_16x16x32_bf16 v[54:57], v[184:187], v[216:219], v[54:57]
	v_mfma_f32_16x16x32_bf16 v[58:61], v[184:187], v[224:227], v[58:61]
	v_mfma_f32_16x16x32_bf16 v[62:65], v[184:187], v[252:255], v[62:65]
	s_waitcnt vmcnt(4)
	s_barrier
	ds_read_b128 v[92:95], v84 offset:32768
	ds_read_b128 v[100:103], v84 offset:34816
	ds_read_b128 v[148:151], v84 offset:36864
	ds_read_b128 v[180:183], v84 offset:38912
	ds_read_b128 v[96:99], v86 offset:32768
	ds_read_b128 v[144:147], v86 offset:34816
	ds_read_b128 v[152:155], v86 offset:36864
	ds_read_b128 v[184:187], v86 offset:38912
	s_waitcnt lgkmcnt(0)
	s_barrier
	s_mov_b32 m0, s6
	v_lshl_add_u64 v[82:83], v[66:67], 0, s[26:27]
	v_mfma_f32_16x16x32_bf16 v[104:107], v[92:95], v[188:191], v[104:107]
	global_load_lds_dwordx4 v[82:83], off
	v_lshl_add_u64 v[66:67], v[66:67], 0, s[34:35]
	v_mfma_f32_16x16x32_bf16 v[108:111], v[92:95], v[212:215], v[108:111]
	v_mfma_f32_16x16x32_bf16 v[112:115], v[92:95], v[220:223], v[112:115]
	v_mfma_f32_16x16x32_bf16 v[116:119], v[92:95], v[228:231], v[116:119]
	v_mfma_f32_16x16x32_bf16 v[128:131], v[100:103], v[188:191], v[128:131]
	v_mfma_f32_16x16x32_bf16 v[132:135], v[100:103], v[212:215], v[132:135]
	s_mov_b32 m0, s13
	v_lshl_add_u64 v[82:83], v[70:71], 0, s[26:27]
	v_mfma_f32_16x16x32_bf16 v[136:139], v[100:103], v[220:223], v[136:139]
	global_load_lds_dwordx4 v[82:83], off
	v_lshl_add_u64 v[70:71], v[70:71], 0, s[34:35]
	v_mfma_f32_16x16x32_bf16 v[140:143], v[100:103], v[228:231], v[140:143]
	v_mfma_f32_16x16x32_bf16 v[196:199], v[148:151], v[188:191], v[196:199]
	v_mfma_f32_16x16x32_bf16 v[200:203], v[148:151], v[212:215], v[200:203]
	v_mfma_f32_16x16x32_bf16 v[204:207], v[148:151], v[220:223], v[204:207]
	v_mfma_f32_16x16x32_bf16 v[208:211], v[148:151], v[228:231], v[208:211]
	v_mfma_f32_16x16x32_bf16 v[236:239], v[180:183], v[188:191], v[236:239]
	v_mfma_f32_16x16x32_bf16 v[240:243], v[180:183], v[212:215], v[240:243]
	v_mfma_f32_16x16x32_bf16 v[244:247], v[180:183], v[220:223], v[244:247]
	v_mfma_f32_16x16x32_bf16 v[248:251], v[180:183], v[228:231], v[248:251]
	s_mov_b32 m0, s15
	v_lshl_add_u64 v[82:83], v[74:75], 0, s[26:27]
	v_mfma_f32_16x16x32_bf16 v[104:107], v[96:99], v[192:195], v[104:107]
	global_load_lds_dwordx4 v[82:83], off
	v_lshl_add_u64 v[74:75], v[74:75], 0, s[34:35]
	v_mfma_f32_16x16x32_bf16 v[108:111], v[96:99], v[216:219], v[108:111]
	v_mfma_f32_16x16x32_bf16 v[112:115], v[96:99], v[224:227], v[112:115]
	v_mfma_f32_16x16x32_bf16 v[116:119], v[96:99], v[252:255], v[116:119]
	v_mfma_f32_16x16x32_bf16 v[128:131], v[144:147], v[192:195], v[128:131]
	v_mfma_f32_16x16x32_bf16 v[132:135], v[144:147], v[216:219], v[132:135]
	s_mov_b32 m0, s17
	v_lshl_add_u64 v[82:83], v[78:79], 0, s[26:27]
	v_mfma_f32_16x16x32_bf16 v[136:139], v[144:147], v[224:227], v[136:139]
	global_load_lds_dwordx4 v[82:83], off
	v_lshl_add_u64 v[78:79], v[78:79], 0, s[34:35]
	v_mfma_f32_16x16x32_bf16 v[140:143], v[144:147], v[252:255], v[140:143]
	v_mfma_f32_16x16x32_bf16 v[196:199], v[152:155], v[192:195], v[196:199]
	v_mfma_f32_16x16x32_bf16 v[200:203], v[152:155], v[216:219], v[200:203]
	v_mfma_f32_16x16x32_bf16 v[204:207], v[152:155], v[224:227], v[204:207]
	v_mfma_f32_16x16x32_bf16 v[208:211], v[152:155], v[252:255], v[208:211]
	v_mfma_f32_16x16x32_bf16 v[236:239], v[184:187], v[192:195], v[236:239]
	v_mfma_f32_16x16x32_bf16 v[240:243], v[184:187], v[216:219], v[240:243]
	v_mfma_f32_16x16x32_bf16 v[244:247], v[184:187], v[224:227], v[244:247]
	v_mfma_f32_16x16x32_bf16 v[248:251], v[184:187], v[252:255], v[248:251]
	s_waitcnt vmcnt(4)
	s_barrier
	ds_read_b128 v[92:95], v84 offset:0
	ds_read_b128 v[100:103], v84 offset:2048
	ds_read_b128 v[148:151], v84 offset:4096
	ds_read_b128 v[180:183], v84 offset:6144
	ds_read_b128 v[188:191], v85 offset:32768
	ds_read_b128 v[212:215], v85 offset:34816
	ds_read_b128 v[220:223], v85 offset:36864
	ds_read_b128 v[228:231], v85 offset:38912
	ds_read_b128 v[96:99], v86 offset:0
	ds_read_b128 v[144:147], v86 offset:2048
	ds_read_b128 v[152:155], v86 offset:4096
	ds_read_b128 v[184:187], v86 offset:6144
	ds_read_b128 v[192:195], v87 offset:32768
	ds_read_b128 v[216:219], v87 offset:34816
	ds_read_b128 v[224:227], v87 offset:36864
	ds_read_b128 v[252:255], v87 offset:38912
	s_waitcnt lgkmcnt(0)
	s_barrier
	v_mfma_f32_16x16x32_bf16 v[2:5], v[92:95], v[188:191], v[2:5]
	v_mfma_f32_16x16x32_bf16 v[6:9], v[92:95], v[212:215], v[6:9]
	v_mfma_f32_16x16x32_bf16 v[10:13], v[92:95], v[220:223], v[10:13]
	v_mfma_f32_16x16x32_bf16 v[14:17], v[92:95], v[228:231], v[14:17]
	v_mfma_f32_16x16x32_bf16 v[18:21], v[100:103], v[188:191], v[18:21]
	v_mfma_f32_16x16x32_bf16 v[22:25], v[100:103], v[212:215], v[22:25]
	v_mfma_f32_16x16x32_bf16 v[26:29], v[100:103], v[220:223], v[26:29]
	v_mfma_f32_16x16x32_bf16 v[30:33], v[100:103], v[228:231], v[30:33]
	v_mfma_f32_16x16x32_bf16 v[34:37], v[148:151], v[188:191], v[34:37]
	v_mfma_f32_16x16x32_bf16 v[38:41], v[148:151], v[212:215], v[38:41]
	v_mfma_f32_16x16x32_bf16 v[42:45], v[148:151], v[220:223], v[42:45]
	v_mfma_f32_16x16x32_bf16 v[46:49], v[148:151], v[228:231], v[46:49]
	v_mfma_f32_16x16x32_bf16 v[50:53], v[180:183], v[188:191], v[50:53]
	v_mfma_f32_16x16x32_bf16 v[54:57], v[180:183], v[212:215], v[54:57]
	v_mfma_f32_16x16x32_bf16 v[58:61], v[180:183], v[220:223], v[58:61]
	v_mfma_f32_16x16x32_bf16 v[62:65], v[180:183], v[228:231], v[62:65]
	v_mfma_f32_16x16x32_bf16 v[2:5], v[96:99], v[192:195], v[2:5]
	v_mfma_f32_16x16x32_bf16 v[6:9], v[96:99], v[216:219], v[6:9]
	v_mfma_f32_16x16x32_bf16 v[10:13], v[96:99], v[224:227], v[10:13]
	v_mfma_f32_16x16x32_bf16 v[14:17], v[96:99], v[252:255], v[14:17]
	v_mfma_f32_16x16x32_bf16 v[18:21], v[144:147], v[192:195], v[18:21]
	v_mfma_f32_16x16x32_bf16 v[22:25], v[144:147], v[216:219], v[22:25]
	v_mfma_f32_16x16x32_bf16 v[26:29], v[144:147], v[224:227], v[26:29]
	v_mfma_f32_16x16x32_bf16 v[30:33], v[144:147], v[252:255], v[30:33]
	v_mfma_f32_16x16x32_bf16 v[34:37], v[152:155], v[192:195], v[34:37]
	v_mfma_f32_16x16x32_bf16 v[38:41], v[152:155], v[216:219], v[38:41]
	v_mfma_f32_16x16x32_bf16 v[42:45], v[152:155], v[224:227], v[42:45]
	v_mfma_f32_16x16x32_bf16 v[46:49], v[152:155], v[252:255], v[46:49]
	v_mfma_f32_16x16x32_bf16 v[50:53], v[184:187], v[192:195], v[50:53]
	v_mfma_f32_16x16x32_bf16 v[54:57], v[184:187], v[216:219], v[54:57]
	v_mfma_f32_16x16x32_bf16 v[58:61], v[184:187], v[224:227], v[58:61]
	v_mfma_f32_16x16x32_bf16 v[62:65], v[184:187], v[252:255], v[62:65]
	s_waitcnt vmcnt(0)
	s_barrier
	ds_read_b128 v[92:95], v84 offset:32768
	ds_read_b128 v[100:103], v84 offset:34816
	ds_read_b128 v[148:151], v84 offset:36864
	ds_read_b128 v[180:183], v84 offset:38912
	ds_read_b128 v[96:99], v86 offset:32768
	ds_read_b128 v[144:147], v86 offset:34816
	ds_read_b128 v[152:155], v86 offset:36864
	ds_read_b128 v[184:187], v86 offset:38912
	s_waitcnt lgkmcnt(0)
	s_barrier
	v_mfma_f32_16x16x32_bf16 v[104:107], v[92:95], v[188:191], v[104:107]
	v_mfma_f32_16x16x32_bf16 v[108:111], v[92:95], v[212:215], v[108:111]
	v_mfma_f32_16x16x32_bf16 v[112:115], v[92:95], v[220:223], v[112:115]
	v_mfma_f32_16x16x32_bf16 v[116:119], v[92:95], v[228:231], v[116:119]
	v_mfma_f32_16x16x32_bf16 v[128:131], v[100:103], v[188:191], v[128:131]
	v_mfma_f32_16x16x32_bf16 v[132:135], v[100:103], v[212:215], v[132:135]
	v_mfma_f32_16x16x32_bf16 v[136:139], v[100:103], v[220:223], v[136:139]
	v_mfma_f32_16x16x32_bf16 v[140:143], v[100:103], v[228:231], v[140:143]
	v_mfma_f32_16x16x32_bf16 v[196:199], v[148:151], v[188:191], v[196:199]
	v_mfma_f32_16x16x32_bf16 v[200:203], v[148:151], v[212:215], v[200:203]
	v_mfma_f32_16x16x32_bf16 v[204:207], v[148:151], v[220:223], v[204:207]
	v_mfma_f32_16x16x32_bf16 v[208:211], v[148:151], v[228:231], v[208:211]
	v_mfma_f32_16x16x32_bf16 v[236:239], v[180:183], v[188:191], v[236:239]
	v_mfma_f32_16x16x32_bf16 v[240:243], v[180:183], v[212:215], v[240:243]
	v_mfma_f32_16x16x32_bf16 v[244:247], v[180:183], v[220:223], v[244:247]
	v_mfma_f32_16x16x32_bf16 v[248:251], v[180:183], v[228:231], v[248:251]
	v_mfma_f32_16x16x32_bf16 v[104:107], v[96:99], v[192:195], v[104:107]
	v_mfma_f32_16x16x32_bf16 v[108:111], v[96:99], v[216:219], v[108:111]
	v_mfma_f32_16x16x32_bf16 v[112:115], v[96:99], v[224:227], v[112:115]
	v_mfma_f32_16x16x32_bf16 v[116:119], v[96:99], v[252:255], v[116:119]
	v_mfma_f32_16x16x32_bf16 v[128:131], v[144:147], v[192:195], v[128:131]
	v_mfma_f32_16x16x32_bf16 v[132:135], v[144:147], v[216:219], v[132:135]
	v_mfma_f32_16x16x32_bf16 v[136:139], v[144:147], v[224:227], v[136:139]
	v_mfma_f32_16x16x32_bf16 v[140:143], v[144:147], v[252:255], v[140:143]
	v_mfma_f32_16x16x32_bf16 v[196:199], v[152:155], v[192:195], v[196:199]
	v_mfma_f32_16x16x32_bf16 v[200:203], v[152:155], v[216:219], v[200:203]
	v_mfma_f32_16x16x32_bf16 v[204:207], v[152:155], v[224:227], v[204:207]
	v_mfma_f32_16x16x32_bf16 v[208:211], v[152:155], v[252:255], v[208:211]
	v_mfma_f32_16x16x32_bf16 v[236:239], v[184:187], v[192:195], v[236:239]
	v_mfma_f32_16x16x32_bf16 v[240:243], v[184:187], v[216:219], v[240:243]
	v_mfma_f32_16x16x32_bf16 v[244:247], v[184:187], v[224:227], v[244:247]
	v_mfma_f32_16x16x32_bf16 v[248:251], v[184:187], v[252:255], v[248:251]
	s_waitcnt vmcnt(0) lgkmcnt(0)
	s_barrier
	s_branch .Lm16_conv
.Lg1_loop_w1:
	ds_read_b128 v[92:95], v84 offset:0
	ds_read_b128 v[100:103], v84 offset:2048
	ds_read_b128 v[148:151], v84 offset:4096
	ds_read_b128 v[180:183], v84 offset:6144
	ds_read_b128 v[188:191], v85 offset:0
	ds_read_b128 v[212:215], v85 offset:2048
	ds_read_b128 v[220:223], v85 offset:4096
	ds_read_b128 v[228:231], v85 offset:6144
	ds_read_b128 v[96:99], v86 offset:0
	ds_read_b128 v[144:147], v86 offset:2048
	ds_read_b128 v[152:155], v86 offset:4096
	ds_read_b128 v[184:187], v86 offset:6144
	ds_read_b128 v[192:195], v87 offset:0
	ds_read_b128 v[216:219], v87 offset:2048
	ds_read_b128 v[224:227], v87 offset:4096
	ds_read_b128 v[252:255], v87 offset:6144
	s_waitcnt lgkmcnt(0)
	s_barrier
	v_mfma_f32_16x16x32_bf16 v[2:5], v[92:95], v[188:191], v[2:5]
	v_mfma_f32_16x16x32_bf16 v[6:9], v[92:95], v[212:215], v[6:9]
	s_mov_b32 m0, s1
	v_mfma_f32_16x16x32_bf16 v[10:13], v[92:95], v[220:223], v[10:13]
	global_load_lds_dwordx4 v[66:67], off
	v_mfma_f32_16x16x32_bf16 v[14:17], v[92:95], v[228:231], v[14:17]
	v_mfma_f32_16x16x32_bf16 v[18:21], v[100:103], v[188:191], v[18:21]
	v_mfma_f32_16x16x32_bf16 v[22:25], v[100:103], v[212:215], v[22:25]
	s_add_i32 m0, s1, 0x400
	v_mfma_f32_16x16x32_bf16 v[26:29], v[100:103], v[220:223], v[26:29]
	global_load_lds_dwordx4 v[70:71], off
	v_mfma_f32_16x16x32_bf16 v[30:33], v[100:103], v[228:231], v[30:33]
	v_mfma_f32_16x16x32_bf16 v[34:37], v[148:151], v[188:191], v[34:37]
	v_mfma_f32_16x16x32_bf16 v[38:41], v[148:151], v[212:215], v[38:41]
	v_mfma_f32_16x16x32_bf16 v[42:45], v[148:151], v[220:223], v[42:45]
	v_mfma_f32_16x16x32_bf16 v[46:49], v[148:151], v[228:231], v[46:49]
	s_add_i32 m0, s1, 0x800
	v_mfma_f32_16x16x32_bf16 v[50:53], v[180:183], v[188:191], v[50:53]
	global_load_lds_dwordx4 v[74:75], off
	v_mfma_f32_16x16x32_bf16 v[54:57], v[180:183], v[212:215], v[54:57]
	v_mfma_f32_16x16x32_bf16 v[58:61], v[180:183], v[220:223], v[58:61]
	v_mfma_f32_16x16x32_bf16 v[62:65], v[180:183], v[228:231], v[62:65]
	v_mfma_f32_16x16x32_bf16 v[2:5], v[96:99], v[192:195], v[2:5]
	v_mfma_f32_16x16x32_bf16 v[6:9], v[96:99], v[216:219], v[6:9]
	s_add_i32 m0, s1, 0xc00
	v_mfma_f32_16x16x32_bf16 v[10:13], v[96:99], v[224:227], v[10:13]
	global_load_lds_dwordx4 v[78:79], off
	v_mfma_f32_16x16x32_bf16 v[14:17], v[96:99], v[252:255], v[14:17]
	v_mfma_f32_16x16x32_bf16 v[18:21], v[144:147], v[192:195], v[18:21]
	v_mfma_f32_16x16x32_bf16 v[22:25], v[144:147], v[216:219], v[22:25]
	s_mov_b32 m0, s8
	v_mfma_f32_16x16x32_bf16 v[26:29], v[144:147], v[224:227], v[26:29]
	global_load_lds_dwordx4 v[68:69], off
	v_lshl_add_u64 v[68:69], v[68:69], 0, s[34:35]
	v_mfma_f32_16x16x32_bf16 v[30:33], v[144:147], v[252:255], v[30:33]
	v_mfma_f32_16x16x32_bf16 v[34:37], v[152:155], v[192:195], v[34:37]
	v_mfma_f32_16x16x32_bf16 v[38:41], v[152:155], v[216:219], v[38:41]
	v_mfma_f32_16x16x32_bf16 v[42:45], v[152:155], v[224:227], v[42:45]
	v_mfma_f32_16x16x32_bf16 v[46:49], v[152:155], v[252:255], v[46:49]
	s_mov_b32 m0, s9
	v_mfma_f32_16x16x32_bf16 v[50:53], v[184:187], v[192:195], v[50:53]
	global_load_lds_dwordx4 v[72:73], off
	v_lshl_add_u64 v[72:73], v[72:73], 0, s[34:35]
	v_mfma_f32_16x16x32_bf16 v[54:57], v[184:187], v[216:219], v[54:57]
	v_mfma_f32_16x16x32_bf16 v[58:61], v[184:187], v[224:227], v[58:61]
	v_mfma_f32_16x16x32_bf16 v[62:65], v[184:187], v[252:255], v[62:65]
	s_waitcnt vmcnt(6)
	s_barrier
	ds_read_b128 v[92:95], v84 offset:32768
	ds_read_b128 v[100:103], v84 offset:34816
	ds_read_b128 v[148:151], v84 offset:36864
	ds_read_b128 v[180:183], v84 offset:38912
	ds_read_b128 v[96:99], v86 offset:32768
	ds_read_b128 v[144:147], v86 offset:34816
	ds_read_b128 v[152:155], v86 offset:36864
	ds_read_b128 v[184:187], v86 offset:38912
	s_waitcnt lgkmcnt(0)
	s_barrier
	v_mfma_f32_16x16x32_bf16 v[104:107], v[92:95], v[188:191], v[104:107]
	v_mfma_f32_16x16x32_bf16 v[108:111], v[92:95], v[212:215], v[108:111]
	s_mov_b32 m0, s6
	v_lshl_add_u64 v[82:83], v[66:67], 0, s[26:27]
	v_mfma_f32_16x16x32_bf16 v[112:115], v[92:95], v[220:223], v[112:115]
	global_load_lds_dwordx4 v[82:83], off
	v_lshl_add_u64 v[66:67], v[66:67], 0, s[34:35]
	v_mfma_f32_16x16x32_bf16 v[116:119], v[92:95], v[228:231], v[116:119]
	v_mfma_f32_16x16x32_bf16 v[128:131], v[100:103], v[188:191], v[128:131]
	v_mfma_f32_16x16x32_bf16 v[132:135], v[100:103], v[212:215], v[132:135]
	s_mov_b32 m0, s13
	v_lshl_add_u64 v[82:83], v[70:71], 0, s[26:27]
	v_mfma_f32_16x16x32_bf16 v[136:139], v[100:103], v[220:223], v[136:139]
	global_load_lds_dwordx4 v[82:83], off
	v_lshl_add_u64 v[70:71], v[70:71], 0, s[34:35]
	v_mfma_f32_16x16x32_bf16 v[140:143], v[100:103], v[228:231], v[140:143]
	v_mfma_f32_16x16x32_bf16 v[196:199], v[148:151], v[188:191], v[196:199]
	v_mfma_f32_16x16x32_bf16 v[200:203], v[148:151], v[212:215], v[200:203]
	v_mfma_f32_16x16x32_bf16 v[204:207], v[148:151], v[220:223], v[204:207]
	v_mfma_f32_16x16x32_bf16 v[208:211], v[148:151], v[228:231], v[208:211]
	s_mov_b32 m0, s15
	v_lshl_add_u64 v[82:83], v[74:75], 0, s[26:27]
	v_mfma_f32_16x16x32_bf16 v[236:239], v[180:183], v[188:191], v[236:239]
	global_load_lds_dwordx4 v[82:83], off
	v_lshl_add_u64 v[74:75], v[74:75], 0, s[34:35]
	v_mfma_f32_16x16x32_bf16 v[240:243], v[180:183], v[212:215], v[240:243]
	v_mfma_f32_16x16x32_bf16 v[244:247], v[180:183], v[220:223], v[244:247]
	v_mfma_f32_16x16x32_bf16 v[248:251], v[180:183], v[228:231], v[248:251]
	v_mfma_f32_16x16x32_bf16 v[104:107], v[96:99], v[192:195], v[104:107]
	v_mfma_f32_16x16x32_bf16 v[108:111], v[96:99], v[216:219], v[108:111]
	s_mov_b32 m0, s17
	v_lshl_add_u64 v[82:83], v[78:79], 0, s[26:27]
	v_mfma_f32_16x16x32_bf16 v[112:115], v[96:99], v[224:227], v[112:115]
	global_load_lds_dwordx4 v[82:83], off
	v_lshl_add_u64 v[78:79], v[78:79], 0, s[34:35]
	v_mfma_f32_16x16x32_bf16 v[116:119], v[96:99], v[252:255], v[116:119]
	v_mfma_f32_16x16x32_bf16 v[128:131], v[144:147], v[192:195], v[128:131]
	v_mfma_f32_16x16x32_bf16 v[132:135], v[144:147], v[216:219], v[132:135]
	s_mov_b32 m0, s10
	v_mfma_f32_16x16x32_bf16 v[136:139], v[144:147], v[224:227], v[136:139]
	global_load_lds_dwordx4 v[76:77], off
	v_lshl_add_u64 v[76:77], v[76:77], 0, s[34:35]
	v_mfma_f32_16x16x32_bf16 v[140:143], v[144:147], v[252:255], v[140:143]
	v_mfma_f32_16x16x32_bf16 v[196:199], v[152:155], v[192:195], v[196:199]
	v_mfma_f32_16x16x32_bf16 v[200:203], v[152:155], v[216:219], v[200:203]
	v_mfma_f32_16x16x32_bf16 v[204:207], v[152:155], v[224:227], v[204:207]
	v_mfma_f32_16x16x32_bf16 v[208:211], v[152:155], v[252:255], v[208:211]
	s_mov_b32 m0, s11
	v_mfma_f32_16x16x32_bf16 v[236:239], v[184:187], v[192:195], v[236:239]
	global_load_lds_dwordx4 v[80:81], off
	v_lshl_add_u64 v[80:81], v[80:81], 0, s[34:35]
	v_mfma_f32_16x16x32_bf16 v[240:243], v[184:187], v[216:219], v[240:243]
	v_mfma_f32_16x16x32_bf16 v[244:247], v[184:187], v[224:227], v[244:247]
	v_mfma_f32_16x16x32_bf16 v[248:251], v[184:187], v[252:255], v[248:251]
	s_waitcnt vmcnt(6)
	s_barrier
	ds_read_b128 v[92:95], v84 offset:0
	ds_read_b128 v[100:103], v84 offset:2048
	ds_read_b128 v[148:151], v84 offset:4096
	ds_read_b128 v[180:183], v84 offset:6144
	ds_read_b128 v[188:191], v85 offset:32768
	ds_read_b128 v[212:215], v85 offset:34816
	ds_read_b128 v[220:223], v85 offset:36864
	ds_read_b128 v[228:231], v85 offset:38912
	ds_read_b128 v[96:99], v86 offset:0
	ds_read_b128 v[144:147], v86 offset:2048
	ds_read_b128 v[152:155], v86 offset:4096
	ds_read_b128 v[184:187], v86 offset:6144
	ds_read_b128 v[192:195], v87 offset:32768
	ds_read_b128 v[216:219], v87 offset:34816
	ds_read_b128 v[224:227], v87 offset:36864
	ds_read_b128 v[252:255], v87 offset:38912
	s_waitcnt lgkmcnt(0)
	s_barrier
	v_mfma_f32_16x16x32_bf16 v[2:5], v[92:95], v[188:191], v[2:5]
	v_mfma_f32_16x16x32_bf16 v[6:9], v[92:95], v[212:215], v[6:9]
	s_mov_b32 m0, s1
	v_mfma_f32_16x16x32_bf16 v[10:13], v[92:95], v[220:223], v[10:13]
	global_load_lds_dwordx4 v[66:67], off
	v_mfma_f32_16x16x32_bf16 v[14:17], v[92:95], v[228:231], v[14:17]
	v_mfma_f32_16x16x32_bf16 v[18:21], v[100:103], v[188:191], v[18:21]
	v_mfma_f32_16x16x32_bf16 v[22:25], v[100:103], v[212:215], v[22:25]
	s_add_i32 m0, s1, 0x400
	v_mfma_f32_16x16x32_bf16 v[26:29], v[100:103], v[220:223], v[26:29]
	global_load_lds_dwordx4 v[70:71], off
	v_mfma_f32_16x16x32_bf16 v[30:33], v[100:103], v[228:231], v[30:33]
	v_mfma_f32_16x16x32_bf16 v[34:37], v[148:151], v[188:191], v[34:37]
	v_mfma_f32_16x16x32_bf16 v[38:41], v[148:151], v[212:215], v[38:41]
	v_mfma_f32_16x16x32_bf16 v[42:45], v[148:151], v[220:223], v[42:45]
	v_mfma_f32_16x16x32_bf16 v[46:49], v[148:151], v[228:231], v[46:49]
	s_add_i32 m0, s1, 0x800
	v_mfma_f32_16x16x32_bf16 v[50:53], v[180:183], v[188:191], v[50:53]
	global_load_lds_dwordx4 v[74:75], off
	v_mfma_f32_16x16x32_bf16 v[54:57], v[180:183], v[212:215], v[54:57]
	v_mfma_f32_16x16x32_bf16 v[58:61], v[180:183], v[220:223], v[58:61]
	v_mfma_f32_16x16x32_bf16 v[62:65], v[180:183], v[228:231], v[62:65]
	v_mfma_f32_16x16x32_bf16 v[2:5], v[96:99], v[192:195], v[2:5]
	v_mfma_f32_16x16x32_bf16 v[6:9], v[96:99], v[216:219], v[6:9]
	s_add_i32 m0, s1, 0xc00
	v_mfma_f32_16x16x32_bf16 v[10:13], v[96:99], v[224:227], v[10:13]
	global_load_lds_dwordx4 v[78:79], off
	v_mfma_f32_16x16x32_bf16 v[14:17], v[96:99], v[252:255], v[14:17]
	v_mfma_f32_16x16x32_bf16 v[18:21], v[144:147], v[192:195], v[18:21]
	v_mfma_f32_16x16x32_bf16 v[22:25], v[144:147], v[216:219], v[22:25]
	s_mov_b32 m0, s7
	v_mfma_f32_16x16x32_bf16 v[26:29], v[144:147], v[224:227], v[26:29]
	global_load_lds_dwordx4 v[68:69], off
	v_lshl_add_u64 v[68:69], v[68:69], 0, s[34:35]
	v_mfma_f32_16x16x32_bf16 v[30:33], v[144:147], v[252:255], v[30:33]
	v_mfma_f32_16x16x32_bf16 v[34:37], v[152:155], v[192:195], v[34:37]
	v_mfma_f32_16x16x32_bf16 v[38:41], v[152:155], v[216:219], v[38:41]
	v_mfma_f32_16x16x32_bf16 v[42:45], v[152:155], v[224:227], v[42:45]
	v_mfma_f32_16x16x32_bf16 v[46:49], v[152:155], v[252:255], v[46:49]
	s_mov_b32 m0, s14
	v_mfma_f32_16x16x32_bf16 v[50:53], v[184:187], v[192:195], v[50:53]
	global_load_lds_dwordx4 v[72:73], off
	v_lshl_add_u64 v[72:73], v[72:73], 0, s[34:35]
	v_mfma_f32_16x16x32_bf16 v[54:57], v[184:187], v[216:219], v[54:57]
	v_mfma_f32_16x16x32_bf16 v[58:61], v[184:187], v[224:227], v[58:61]
	v_mfma_f32_16x16x32_bf16 v[62:65], v[184:187], v[252:255], v[62:65]
	s_waitcnt vmcnt(6)
	s_barrier
	ds_read_b128 v[92:95], v84 offset:32768
	ds_read_b128 v[100:103], v84 offset:34816
	ds_read_b128 v[148:151], v84 offset:36864
	ds_read_b128 v[180:183], v84 offset:38912
	ds_read_b128 v[96:99], v86 offset:32768
	ds_read_b128 v[144:147], v86 offset:34816
	ds_read_b128 v[152:155], v86 offset:36864
	ds_read_b128 v[184:187], v86 offset:38912
	s_waitcnt lgkmcnt(0)
	s_barrier
	v_mfma_f32_16x16x32_bf16 v[104:107], v[92:95], v[188:191], v[104:107]
	v_mfma_f32_16x16x32_bf16 v[108:111], v[92:95], v[212:215], v[108:111]
	s_mov_b32 m0, s6
	v_lshl_add_u64 v[82:83], v[66:67], 0, s[26:27]
	v_mfma_f32_16x16x32_bf16 v[112:115], v[92:95], v[220:223], v[112:115]
	global_load_lds_dwordx4 v[82:83], off
	v_lshl_add_u64 v[66:67], v[66:67], 0, s[34:35]
	v_mfma_f32_16x16x32_bf16 v[116:119], v[92:95], v[228:231], v[116:119]
	v_mfma_f32_16x16x32_bf16 v[128:131], v[100:103], v[188:191], v[128:131]
	v_mfma_f32_16x16x32_bf16 v[132:135], v[100:103], v[212:215], v[132:135]
	s_mov_b32 m0, s13
	v_lshl_add_u64 v[82:83], v[70:71], 0, s[26:27]
	v_mfma_f32_16x16x32_bf16 v[136:139], v[100:103], v[220:223], v[136:139]
	global_load_lds_dwordx4 v[82:83], off
	v_lshl_add_u64 v[70:71], v[70:71], 0, s[34:35]
	v_mfma_f32_16x16x32_bf16 v[140:143], v[100:103], v[228:231], v[140:143]
	v_mfma_f32_16x16x32_bf16 v[196:199], v[148:151], v[188:191], v[196:199]
	v_mfma_f32_16x16x32_bf16 v[200:203], v[148:151], v[212:215], v[200:203]
	v_mfma_f32_16x16x32_bf16 v[204:207], v[148:151], v[220:223], v[204:207]
	v_mfma_f32_16x16x32_bf16 v[208:211], v[148:151], v[228:231], v[208:211]
	s_mov_b32 m0, s15
	v_lshl_add_u64 v[82:83], v[74:75], 0, s[26:27]
	v_mfma_f32_16x16x32_bf16 v[236:239], v[180:183], v[188:191], v[236:239]
	global_load_lds_dwordx4 v[82:83], off
	v_lshl_add_u64 v[74:75], v[74:75], 0, s[34:35]
	v_mfma_f32_16x16x32_bf16 v[240:243], v[180:183], v[212:215], v[240:243]
	v_mfma_f32_16x16x32_bf16 v[244:247], v[180:183], v[220:223], v[244:247]
	v_mfma_f32_16x16x32_bf16 v[248:251], v[180:183], v[228:231], v[248:251]
	v_mfma_f32_16x16x32_bf16 v[104:107], v[96:99], v[192:195], v[104:107]
	v_mfma_f32_16x16x32_bf16 v[108:111], v[96:99], v[216:219], v[108:111]
	s_mov_b32 m0, s17
	v_lshl_add_u64 v[82:83], v[78:79], 0, s[26:27]
	v_mfma_f32_16x16x32_bf16 v[112:115], v[96:99], v[224:227], v[112:115]
	global_load_lds_dwordx4 v[82:83], off
	v_lshl_add_u64 v[78:79], v[78:79], 0, s[34:35]
	v_mfma_f32_16x16x32_bf16 v[116:119], v[96:99], v[252:255], v[116:119]
	v_mfma_f32_16x16x32_bf16 v[128:131], v[144:147], v[192:195], v[128:131]
	v_mfma_f32_16x16x32_bf16 v[132:135], v[144:147], v[216:219], v[132:135]
	s_mov_b32 m0, s16
	v_mfma_f32_16x16x32_bf16 v[136:139], v[144:147], v[224:227], v[136:139]
	global_load_lds_dwordx4 v[76:77], off
	v_lshl_add_u64 v[76:77], v[76:77], 0, s[34:35]
	v_mfma_f32_16x16x32_bf16 v[140:143], v[144:147], v[252:255], v[140:143]
	v_mfma_f32_16x16x32_bf16 v[196:199], v[152:155], v[192:195], v[196:199]
	v_mfma_f32_16x16x32_bf16 v[200:203], v[152:155], v[216:219], v[200:203]
	v_mfma_f32_16x16x32_bf16 v[204:207], v[152:155], v[224:227], v[204:207]
	v_mfma_f32_16x16x32_bf16 v[208:211], v[152:155], v[252:255], v[208:211]
	s_mov_b32 m0, s25
	v_mfma_f32_16x16x32_bf16 v[236:239], v[184:187], v[192:195], v[236:239]
	global_load_lds_dwordx4 v[80:81], off
	v_lshl_add_u64 v[80:81], v[80:81], 0, s[34:35]
	v_mfma_f32_16x16x32_bf16 v[240:243], v[184:187], v[216:219], v[240:243]
	v_mfma_f32_16x16x32_bf16 v[244:247], v[184:187], v[224:227], v[244:247]
	v_mfma_f32_16x16x32_bf16 v[248:251], v[184:187], v[252:255], v[248:251]
	s_waitcnt vmcnt(6)
	s_barrier
	s_add_i32 s12, s12, 2
	s_cmp_lt_u32 s12, 14
	s_cbranch_scc1 .Lg1_loop_w1
	ds_read_b128 v[92:95], v84 offset:0
	ds_read_b128 v[100:103], v84 offset:2048
	ds_read_b128 v[148:151], v84 offset:4096
	ds_read_b128 v[180:183], v84 offset:6144
	ds_read_b128 v[188:191], v85 offset:0
	ds_read_b128 v[212:215], v85 offset:2048
	ds_read_b128 v[220:223], v85 offset:4096
	ds_read_b128 v[228:231], v85 offset:6144
	ds_read_b128 v[96:99], v86 offset:0
	ds_read_b128 v[144:147], v86 offset:2048
	ds_read_b128 v[152:155], v86 offset:4096
	ds_read_b128 v[184:187], v86 offset:6144
	ds_read_b128 v[192:195], v87 offset:0
	ds_read_b128 v[216:219], v87 offset:2048
	ds_read_b128 v[224:227], v87 offset:4096
	ds_read_b128 v[252:255], v87 offset:6144
	s_waitcnt lgkmcnt(0)
	s_barrier
	v_mfma_f32_16x16x32_bf16 v[2:5], v[92:95], v[188:191], v[2:5]
	v_mfma_f32_16x16x32_bf16 v[6:9], v[92:95], v[212:215], v[6:9]
	s_mov_b32 m0, s1
	v_mfma_f32_16x16x32_bf16 v[10:13], v[92:95], v[220:223], v[10:13]
	global_load_lds_dwordx4 v[66:67], off
	v_mfma_f32_16x16x32_bf16 v[14:17], v[92:95], v[228:231], v[14:17]
	v_mfma_f32_16x16x32_bf16 v[18:21], v[100:103], v[188:191], v[18:21]
	v_mfma_f32_16x16x32_bf16 v[22:25], v[100:103], v[212:215], v[22:25]
	s_add_i32 m0, s1, 0x400
	v_mfma_f32_16x16x32_bf16 v[26:29], v[100:103], v[220:223], v[26:29]
	global_load_lds_dwordx4 v[70:71], off
	v_mfma_f32_16x16x32_bf16 v[30:33], v[100:103], v[228:231], v[30:33]
	v_mfma_f32_16x16x32_bf16 v[34:37], v[148:151], v[188:191], v[34:37]
	v_mfma_f32_16x16x32_bf16 v[38:41], v[148:151], v[212:215], v[38:41]
	v_mfma_f32_16x16x32_bf16 v[42:45], v[148:151], v[220:223], v[42:45]
	v_mfma_f32_16x16x32_bf16 v[46:49], v[148:151], v[228:231], v[46:49]
	v_mfma_f32_16x16x32_bf16 v[50:53], v[180:183], v[188:191], v[50:53]
	v_mfma_f32_16x16x32_bf16 v[54:57], v[180:183], v[212:215], v[54:57]
	v_mfma_f32_16x16x32_bf16 v[58:61], v[180:183], v[220:223], v[58:61]
	v_mfma_f32_16x16x32_bf16 v[62:65], v[180:183], v[228:231], v[62:65]
	v_mfma_f32_16x16x32_bf16 v[2:5], v[96:99], v[192:195], v[2:5]
	v_mfma_f32_16x16x32_bf16 v[6:9], v[96:99], v[216:219], v[6:9]
	s_add_i32 m0, s1, 0x800
	v_mfma_f32_16x16x32_bf16 v[10:13], v[96:99], v[224:227], v[10:13]
	global_load_lds_dwordx4 v[74:75], off
	v_mfma_f32_16x16x32_bf16 v[14:17], v[96:99], v[252:255], v[14:17]
	v_mfma_f32_16x16x32_bf16 v[18:21], v[144:147], v[192:195], v[18:21]
	v_mfma_f32_16x16x32_bf16 v[22:25], v[144:147], v[216:219], v[22:25]
	s_add_i32 m0, s1, 0xc00
	v_mfma_f32_16x16x32_bf16 v[26:29], v[144:147], v[224:227], v[26:29]
	global_load_lds_dwordx4 v[78:79], off
	v_mfma_f32_16x16x32_bf16 v[30:33], v[144:147], v[252:255], v[30:33]
	v_mfma_f32_16x16x32_bf16 v[34:37], v[152:155], v[192:195], v[34:37]
	v_mfma_f32_16x16x32_bf16 v[38:41], v[152:155], v[216:219], v[38:41]
	v_mfma_f32_16x16x32_bf16 v[42:45], v[152:155], v[224:227], v[42:45]
	v_mfma_f32_16x16x32_bf16 v[46:49], v[152:155], v[252:255], v[46:49]
	v_mfma_f32_16x16x32_bf16 v[50:53], v[184:187], v[192:195], v[50:53]
	v_mfma_f32_16x16x32_bf16 v[54:57], v[184:187], v[216:219], v[54:57]
	v_mfma_f32_16x16x32_bf16 v[58:61], v[184:187], v[224:227], v[58:61]
	v_mfma_f32_16x16x32_bf16 v[62:65], v[184:187], v[252:255], v[62:65]
	s_waitcnt vmcnt(4)
	s_barrier
	ds_read_b128 v[92:95], v84 offset:32768
	ds_read_b128 v[100:103], v84 offset:34816
	ds_read_b128 v[148:151], v84 offset:36864
	ds_read_b128 v[180:183], v84 offset:38912
	ds_read_b128 v[96:99], v86 offset:32768
	ds_read_b128 v[144:147], v86 offset:34816
	ds_read_b128 v[152:155], v86 offset:36864
	ds_read_b128 v[184:187], v86 offset:38912
	s_waitcnt lgkmcnt(0)
	s_barrier
	v_mfma_f32_16x16x32_bf16 v[104:107], v[92:95], v[188:191], v[104:107]
	v_mfma_f32_16x16x32_bf16 v[108:111], v[92:95], v[212:215], v[108:111]
	s_mov_b32 m0, s6
	v_lshl_add_u64 v[82:83], v[66:67], 0, s[26:27]
	v_mfma_f32_16x16x32_bf16 v[112:115], v[92:95], v[220:223], v[112:115]
	global_load_lds_dwordx4 v[82:83], off
	v_lshl_add_u64 v[66:67], v[66:67], 0, s[34:35]
	v_mfma_f32_16x16x32_bf16 v[116:119], v[92:95], v[228:231], v[116:119]
	v_mfma_f32_16x16x32_bf16 v[128:131], v[100:103], v[188:191], v[128:131]
	v_mfma_f32_16x16x32_bf16 v[132:135], v[100:103], v[212:215], v[132:135]
	s_mov_b32 m0, s13
	v_lshl_add_u64 v[82:83], v[70:71], 0, s[26:27]
	v_mfma_f32_16x16x32_bf16 v[136:139], v[100:103], v[220:223], v[136:139]
	global_load_lds_dwordx4 v[82:83], off
	v_lshl_add_u64 v[70:71], v[70:71], 0, s[34:35]
	v_mfma_f32_16x16x32_bf16 v[140:143], v[100:103], v[228:231], v[140:143]
	v_mfma_f32_16x16x32_bf16 v[196:199], v[148:151], v[188:191], v[196:199]
	v_mfma_f32_16x16x32_bf16 v[200:203], v[148:151], v[212:215], v[200:203]
	v_mfma_f32_16x16x32_bf16 v[204:207], v[148:151], v[220:223], v[204:207]
	v_mfma_f32_16x16x32_bf16 v[208:211], v[148:151], v[228:231], v[208:211]
	v_mfma_f32_16x16x32_bf16 v[236:239], v[180:183], v[188:191], v[236:239]
	v_mfma_f32_16x16x32_bf16 v[240:243], v[180:183], v[212:215], v[240:243]
	v_mfma_f32_16x16x32_bf16 v[244:247], v[180:183], v[220:223], v[244:247]
	v_mfma_f32_16x16x32_bf16 v[248:251], v[180:183], v[228:231], v[248:251]
	v_mfma_f32_16x16x32_bf16 v[104:107], v[96:99], v[192:195], v[104:107]
	v_mfma_f32_16x16x32_bf16 v[108:111], v[96:99], v[216:219], v[108:111]
	s_mov_b32 m0, s15
	v_lshl_add_u64 v[82:83], v[74:75], 0, s[26:27]
	v_mfma_f32_16x16x32_bf16 v[112:115], v[96:99], v[224:227], v[112:115]
	global_load_lds_dwordx4 v[82:83], off
	v_lshl_add_u64 v[74:75], v[74:75], 0, s[34:35]
	v_mfma_f32_16x16x32_bf16 v[116:119], v[96:99], v[252:255], v[116:119]
	v_mfma_f32_16x16x32_bf16 v[128:131], v[144:147], v[192:195], v[128:131]
	v_mfma_f32_16x16x32_bf16 v[132:135], v[144:147], v[216:219], v[132:135]
	s_mov_b32 m0, s17
	v_lshl_add_u64 v[82:83], v[78:79], 0, s[26:27]
	v_mfma_f32_16x16x32_bf16 v[136:139], v[144:147], v[224:227], v[136:139]
	global_load_lds_dwordx4 v[82:83], off
	v_lshl_add_u64 v[78:79], v[78:79], 0, s[34:35]
	v_mfma_f32_16x16x32_bf16 v[140:143], v[144:147], v[252:255], v[140:143]
	v_mfma_f32_16x16x32_bf16 v[196:199], v[152:155], v[192:195], v[196:199]
	v_mfma_f32_16x16x32_bf16 v[200:203], v[152:155], v[216:219], v[200:203]
	v_mfma_f32_16x16x32_bf16 v[204:207], v[152:155], v[224:227], v[204:207]
	v_mfma_f32_16x16x32_bf16 v[208:211], v[152:155], v[252:255], v[208:211]
	v_mfma_f32_16x16x32_bf16 v[236:239], v[184:187], v[192:195], v[236:239]
	v_mfma_f32_16x16x32_bf16 v[240:243], v[184:187], v[216:219], v[240:243]
	v_mfma_f32_16x16x32_bf16 v[244:247], v[184:187], v[224:227], v[244:247]
	v_mfma_f32_16x16x32_bf16 v[248:251], v[184:187], v[252:255], v[248:251]
	s_waitcnt vmcnt(4)
	s_barrier
	ds_read_b128 v[92:95], v84 offset:0
	ds_read_b128 v[100:103], v84 offset:2048
	ds_read_b128 v[148:151], v84 offset:4096
	ds_read_b128 v[180:183], v84 offset:6144
	ds_read_b128 v[188:191], v85 offset:32768
	ds_read_b128 v[212:215], v85 offset:34816
	ds_read_b128 v[220:223], v85 offset:36864
	ds_read_b128 v[228:231], v85 offset:38912
	ds_read_b128 v[96:99], v86 offset:0
	ds_read_b128 v[144:147], v86 offset:2048
	ds_read_b128 v[152:155], v86 offset:4096
	ds_read_b128 v[184:187], v86 offset:6144
	ds_read_b128 v[192:195], v87 offset:32768
	ds_read_b128 v[216:219], v87 offset:34816
	ds_read_b128 v[224:227], v87 offset:36864
	ds_read_b128 v[252:255], v87 offset:38912
	s_waitcnt lgkmcnt(0)
	s_barrier
	v_mfma_f32_16x16x32_bf16 v[2:5], v[92:95], v[188:191], v[2:5]
	v_mfma_f32_16x16x32_bf16 v[6:9], v[92:95], v[212:215], v[6:9]
	v_mfma_f32_16x16x32_bf16 v[10:13], v[92:95], v[220:223], v[10:13]
	v_mfma_f32_16x16x32_bf16 v[14:17], v[92:95], v[228:231], v[14:17]
	v_mfma_f32_16x16x32_bf16 v[18:21], v[100:103], v[188:191], v[18:21]
	v_mfma_f32_16x16x32_bf16 v[22:25], v[100:103], v[212:215], v[22:25]
	v_mfma_f32_16x16x32_bf16 v[26:29], v[100:103], v[220:223], v[26:29]
	v_mfma_f32_16x16x32_bf16 v[30:33], v[100:103], v[228:231], v[30:33]
	v_mfma_f32_16x16x32_bf16 v[34:37], v[148:151], v[188:191], v[34:37]
	v_mfma_f32_16x16x32_bf16 v[38:41], v[148:151], v[212:215], v[38:41]
	v_mfma_f32_16x16x32_bf16 v[42:45], v[148:151], v[220:223], v[42:45]
	v_mfma_f32_16x16x32_bf16 v[46:49], v[148:151], v[228:231], v[46:49]
	v_mfma_f32_16x16x32_bf16 v[50:53], v[180:183], v[188:191], v[50:53]
	v_mfma_f32_16x16x32_bf16 v[54:57], v[180:183], v[212:215], v[54:57]
	v_mfma_f32_16x16x32_bf16 v[58:61], v[180:183], v[220:223], v[58:61]
	v_mfma_f32_16x16x32_bf16 v[62:65], v[180:183], v[228:231], v[62:65]
	v_mfma_f32_16x16x32_bf16 v[2:5], v[96:99], v[192:195], v[2:5]
	v_mfma_f32_16x16x32_bf16 v[6:9], v[96:99], v[216:219], v[6:9]
	v_mfma_f32_16x16x32_bf16 v[10:13], v[96:99], v[224:227], v[10:13]
	v_mfma_f32_16x16x32_bf16 v[14:17], v[96:99], v[252:255], v[14:17]
	v_mfma_f32_16x16x32_bf16 v[18:21], v[144:147], v[192:195], v[18:21]
	v_mfma_f32_16x16x32_bf16 v[22:25], v[144:147], v[216:219], v[22:25]
	v_mfma_f32_16x16x32_bf16 v[26:29], v[144:147], v[224:227], v[26:29]
	v_mfma_f32_16x16x32_bf16 v[30:33], v[144:147], v[252:255], v[30:33]
	v_mfma_f32_16x16x32_bf16 v[34:37], v[152:155], v[192:195], v[34:37]
	v_mfma_f32_16x16x32_bf16 v[38:41], v[152:155], v[216:219], v[38:41]
	v_mfma_f32_16x16x32_bf16 v[42:45], v[152:155], v[224:227], v[42:45]
	v_mfma_f32_16x16x32_bf16 v[46:49], v[152:155], v[252:255], v[46:49]
	v_mfma_f32_16x16x32_bf16 v[50:53], v[184:187], v[192:195], v[50:53]
	v_mfma_f32_16x16x32_bf16 v[54:57], v[184:187], v[216:219], v[54:57]
	v_mfma_f32_16x16x32_bf16 v[58:61], v[184:187], v[224:227], v[58:61]
	v_mfma_f32_16x16x32_bf16 v[62:65], v[184:187], v[252:255], v[62:65]
	s_waitcnt vmcnt(0)
	s_barrier
	ds_read_b128 v[92:95], v84 offset:32768
	ds_read_b128 v[100:103], v84 offset:34816
	ds_read_b128 v[148:151], v84 offset:36864
	ds_read_b128 v[180:183], v84 offset:38912
	ds_read_b128 v[96:99], v86 offset:32768
	ds_read_b128 v[144:147], v86 offset:34816
	ds_read_b128 v[152:155], v86 offset:36864
	ds_read_b128 v[184:187], v86 offset:38912
	s_waitcnt lgkmcnt(0)
	s_barrier
	v_mfma_f32_16x16x32_bf16 v[104:107], v[92:95], v[188:191], v[104:107]
	v_mfma_f32_16x16x32_bf16 v[108:111], v[92:95], v[212:215], v[108:111]
	v_mfma_f32_16x16x32_bf16 v[112:115], v[92:95], v[220:223], v[112:115]
	v_mfma_f32_16x16x32_bf16 v[116:119], v[92:95], v[228:231], v[116:119]
	v_mfma_f32_16x16x32_bf16 v[128:131], v[100:103], v[188:191], v[128:131]
	v_mfma_f32_16x16x32_bf16 v[132:135], v[100:103], v[212:215], v[132:135]
	v_mfma_f32_16x16x32_bf16 v[136:139], v[100:103], v[220:223], v[136:139]
	v_mfma_f32_16x16x32_bf16 v[140:143], v[100:103], v[228:231], v[140:143]
	v_mfma_f32_16x16x32_bf16 v[196:199], v[148:151], v[188:191], v[196:199]
	v_mfma_f32_16x16x32_bf16 v[200:203], v[148:151], v[212:215], v[200:203]
	v_mfma_f32_16x16x32_bf16 v[204:207], v[148:151], v[220:223], v[204:207]
	v_mfma_f32_16x16x32_bf16 v[208:211], v[148:151], v[228:231], v[208:211]
	v_mfma_f32_16x16x32_bf16 v[236:239], v[180:183], v[188:191], v[236:239]
	v_mfma_f32_16x16x32_bf16 v[240:243], v[180:183], v[212:215], v[240:243]
	v_mfma_f32_16x16x32_bf16 v[244:247], v[180:183], v[220:223], v[244:247]
	v_mfma_f32_16x16x32_bf16 v[248:251], v[180:183], v[228:231], v[248:251]
	v_mfma_f32_16x16x32_bf16 v[104:107], v[96:99], v[192:195], v[104:107]
	v_mfma_f32_16x16x32_bf16 v[108:111], v[96:99], v[216:219], v[108:111]
	v_mfma_f32_16x16x32_bf16 v[112:115], v[96:99], v[224:227], v[112:115]
	v_mfma_f32_16x16x32_bf16 v[116:119], v[96:99], v[252:255], v[116:119]
	v_mfma_f32_16x16x32_bf16 v[128:131], v[144:147], v[192:195], v[128:131]
	v_mfma_f32_16x16x32_bf16 v[132:135], v[144:147], v[216:219], v[132:135]
	v_mfma_f32_16x16x32_bf16 v[136:139], v[144:147], v[224:227], v[136:139]
	v_mfma_f32_16x16x32_bf16 v[140:143], v[144:147], v[252:255], v[140:143]
	v_mfma_f32_16x16x32_bf16 v[196:199], v[152:155], v[192:195], v[196:199]
	v_mfma_f32_16x16x32_bf16 v[200:203], v[152:155], v[216:219], v[200:203]
	v_mfma_f32_16x16x32_bf16 v[204:207], v[152:155], v[224:227], v[204:207]
	v_mfma_f32_16x16x32_bf16 v[208:211], v[152:155], v[252:255], v[208:211]
	v_mfma_f32_16x16x32_bf16 v[236:239], v[184:187], v[192:195], v[236:239]
	v_mfma_f32_16x16x32_bf16 v[240:243], v[184:187], v[216:219], v[240:243]
	v_mfma_f32_16x16x32_bf16 v[244:247], v[184:187], v[224:227], v[244:247]
	v_mfma_f32_16x16x32_bf16 v[248:251], v[184:187], v[252:255], v[248:251]
	s_waitcnt vmcnt(0) lgkmcnt(0)
	s_barrier
	s_branch .Lm16_conv
.Lg1_loop_w2:
	ds_read_b128 v[92:95], v84 offset:0
	ds_read_b128 v[100:103], v84 offset:2048
	ds_read_b128 v[148:151], v84 offset:4096
	ds_read_b128 v[180:183], v84 offset:6144
	ds_read_b128 v[188:191], v85 offset:0
	ds_read_b128 v[212:215], v85 offset:2048
	ds_read_b128 v[220:223], v85 offset:4096
	ds_read_b128 v[228:231], v85 offset:6144
	ds_read_b128 v[96:99], v86 offset:0
	ds_read_b128 v[144:147], v86 offset:2048
	ds_read_b128 v[152:155], v86 offset:4096
	ds_read_b128 v[184:187], v86 offset:6144
	ds_read_b128 v[192:195], v87 offset:0
	ds_read_b128 v[216:219], v87 offset:2048
	ds_read_b128 v[224:227], v87 offset:4096
	ds_read_b128 v[252:255], v87 offset:6144
	s_waitcnt lgkmcnt(0)
	s_barrier
	v_mfma_f32_16x16x32_bf16 v[2:5], v[92:95], v[188:191], v[2:5]
	v_mfma_f32_16x16x32_bf16 v[6:9], v[92:95], v[212:215], v[6:9]
	s_mov_b32 m0, s1
	v_mfma_f32_16x16x32_bf16 v[10:13], v[92:95], v[220:223], v[10:13]
	global_load_lds_dwordx4 v[66:67], off
	v_mfma_f32_16x16x32_bf16 v[14:17], v[92:95], v[228:231], v[14:17]
	v_mfma_f32_16x16x32_bf16 v[18:21], v[100:103], v[188:191], v[18:21]
	v_mfma_f32_16x16x32_bf16 v[22:25], v[100:103], v[212:215], v[22:25]
	v_mfma_f32_16x16x32_bf16 v[26:29], v[100:103], v[220:223], v[26:29]
	v_mfma_f32_16x16x32_bf16 v[30:33], v[100:103], v[228:231], v[30:33]
	s_add_i32 m0, s1, 0x400
	v_mfma_f32_16x16x32_bf16 v[34:37], v[148:151], v[188:191], v[34:37]
	global_load_lds_dwordx4 v[70:71], off
	v_mfma_f32_16x16x32_bf16 v[38:41], v[148:151], v[212:215], v[38:41]
	v_mfma_f32_16x16x32_bf16 v[42:45], v[148:151], v[220:223], v[42:45]
	v_mfma_f32_16x16x32_bf16 v[46:49], v[148:151], v[228:231], v[46:49]
	v_mfma_f32_16x16x32_bf16 v[50:53], v[180:183], v[188:191], v[50:53]
	v_mfma_f32_16x16x32_bf16 v[54:57], v[180:183], v[212:215], v[54:57]
	s_add_i32 m0, s1, 0x800
	v_mfma_f32_16x16x32_bf16 v[58:61], v[180:183], v[220:223], v[58:61]
	global_load_lds_dwordx4 v[74:75], off
	v_mfma_f32_16x16x32_bf16 v[62:65], v[180:183], v[228:231], v[62:65]
	v_mfma_f32_16x16x32_bf16 v[2:5], v[96:99], v[192:195], v[2:5]
	v_mfma_f32_16x16x32_bf16 v[6:9], v[96:99], v[216:219], v[6:9]
	s_add_i32 m0, s1, 0xc00
	v_mfma_f32_16x16x32_bf16 v[10:13], v[96:99], v[224:227], v[10:13]
	global_load_lds_dwordx4 v[78:79], off
	v_mfma_f32_16x16x32_bf16 v[14:17], v[96:99], v[252:255], v[14:17]
	v_mfma_f32_16x16x32_bf16 v[18:21], v[144:147], v[192:195], v[18:21]
	v_mfma_f32_16x16x32_bf16 v[22:25], v[144:147], v[216:219], v[22:25]
	v_mfma_f32_16x16x32_bf16 v[26:29], v[144:147], v[224:227], v[26:29]
	v_mfma_f32_16x16x32_bf16 v[30:33], v[144:147], v[252:255], v[30:33]
	s_mov_b32 m0, s8
	v_mfma_f32_16x16x32_bf16 v[34:37], v[152:155], v[192:195], v[34:37]
	global_load_lds_dwordx4 v[68:69], off
	v_lshl_add_u64 v[68:69], v[68:69], 0, s[34:35]
	v_mfma_f32_16x16x32_bf16 v[38:41], v[152:155], v[216:219], v[38:41]
	v_mfma_f32_16x16x32_bf16 v[42:45], v[152:155], v[224:227], v[42:45]
	v_mfma_f32_16x16x32_bf16 v[46:49], v[152:155], v[252:255], v[46:49]
	v_mfma_f32_16x16x32_bf16 v[50:53], v[184:187], v[192:195], v[50:53]
	v_mfma_f32_16x16x32_bf16 v[54:57], v[184:187], v[216:219], v[54:57]
	s_mov_b32 m0, s9
	v_mfma_f32_16x16x32_bf16 v[58:61], v[184:187], v[224:227], v[58:61]
	global_load_lds_dwordx4 v[72:73], off
	v_lshl_add_u64 v[72:73], v[72:73], 0, s[34:35]
	v_mfma_f32_16x16x32_bf16 v[62:65], v[184:187], v[252:255], v[62:65]
	s_waitcnt vmcnt(6)
	s_barrier
	ds_read_b128 v[92:95], v84 offset:32768
	ds_read_b128 v[100:103], v84 offset:34816
	ds_read_b128 v[148:151], v84 offset:36864
	ds_read_b128 v[180:183], v84 offset:38912
	ds_read_b128 v[96:99], v86 offset:32768
	ds_read_b128 v[144:147], v86 offset:34816
	ds_read_b128 v[152:155], v86 offset:36864
	ds_read_b128 v[184:187], v86 offset:38912
	s_waitcnt lgkmcnt(0)
	s_barrier
	v_mfma_f32_16x16x32_bf16 v[104:107], v[92:95], v[188:191], v[104:107]
	v_mfma_f32_16x16x32_bf16 v[108:111], v[92:95], v[212:215], v[108:111]
	s_mov_b32 m0, s6
	v_lshl_add_u64 v[82:83], v[66:67], 0, s[26:27]
	v_mfma_f32_16x16x32_bf16 v[112:115], v[92:95], v[220:223], v[112:115]
	global_load_lds_dwordx4 v[82:83], off
	v_lshl_add_u64 v[66:67], v[66:67], 0, s[34:35]
	v_mfma_f32_16x16x32_bf16 v[116:119], v[92:95], v[228:231], v[116:119]
	v_mfma_f32_16x16x32_bf16 v[128:131], v[100:103], v[188:191], v[128:131]
	v_mfma_f32_16x16x32_bf16 v[132:135], v[100:103], v[212:215], v[132:135]
	v_mfma_f32_16x16x32_bf16 v[136:139], v[100:103], v[220:223], v[136:139]
	v_mfma_f32_16x16x32_bf16 v[140:143], v[100:103], v[228:231], v[140:143]
	s_mov_b32 m0, s13
	v_lshl_add_u64 v[82:83], v[70:71], 0, s[26:27]
	v_mfma_f32_16x16x32_bf16 v[196:199], v[148:151], v[188:191], v[196:199]
	global_load_lds_dwordx4 v[82:83], off
	v_lshl_add_u64 v[70:71], v[70:71], 0, s[34:35]
	v_mfma_f32_16x16x32_bf16 v[200:203], v[148:151], v[212:215], v[200:203]
	v_mfma_f32_16x16x32_bf16 v[204:207], v[148:151], v[220:223], v[204:207]
	v_mfma_f32_16x16x32_bf16 v[208:211], v[148:151], v[228:231], v[208:211]
	v_mfma_f32_16x16x32_bf16 v[236:239], v[180:183], v[188:191], v[236:239]
	v_mfma_f32_16x16x32_bf16 v[240:243], v[180:183], v[212:215], v[240:243]
	s_mov_b32 m0, s15
	v_lshl_add_u64 v[82:83], v[74:75], 0, s[26:27]
	v_mfma_f32_16x16x32_bf16 v[244:247], v[180:183], v[220:223], v[244:247]
	global_load_lds_dwordx4 v[82:83], off
	v_lshl_add_u64 v[74:75], v[74:75], 0, s[34:35]
	v_mfma_f32_16x16x32_bf16 v[248:251], v[180:183], v[228:231], v[248:251]
	v_mfma_f32_16x16x32_bf16 v[104:107], v[96:99], v[192:195], v[104:107]
	v_mfma_f32_16x16x32_bf16 v[108:111], v[96:99], v[216:219], v[108:111]
	s_mov_b32 m0, s17
	v_lshl_add_u64 v[82:83], v[78:79], 0, s[26:27]
	v_mfma_f32_16x16x32_bf16 v[112:115], v[96:99], v[224:227], v[112:115]
	global_load_lds_dwordx4 v[82:83], off
	v_lshl_add_u64 v[78:79], v[78:79], 0, s[34:35]
	v_mfma_f32_16x16x32_bf16 v[116:119], v[96:99], v[252:255], v[116:119]
	v_mfma_f32_16x16x32_bf16 v[128:131], v[144:147], v[192:195], v[128:131]
	v_mfma_f32_16x16x32_bf16 v[132:135], v[144:147], v[216:219], v[132:135]
	v_mfma_f32_16x16x32_bf16 v[136:139], v[144:147], v[224:227], v[136:139]
	v_mfma_f32_16x16x32_bf16 v[140:143], v[144:147], v[252:255], v[140:143]
	s_mov_b32 m0, s10
	v_mfma_f32_16x16x32_bf16 v[196:199], v[152:155], v[192:195], v[196:199]
	global_load_lds_dwordx4 v[76:77], off
	v_lshl_add_u64 v[76:77], v[76:77], 0, s[34:35]
	v_mfma_f32_16x16x32_bf16 v[200:203], v[152:155], v[216:219], v[200:203]
	v_mfma_f32_16x16x32_bf16 v[204:207], v[152:155], v[224:227], v[204:207]
	v_mfma_f32_16x16x32_bf16 v[208:211], v[152:155], v[252:255], v[208:211]
	v_mfma_f32_16x16x32_bf16 v[236:239], v[184:187], v[192:195], v[236:239]
	v_mfma_f32_16x16x32_bf16 v[240:243], v[184:187], v[216:219], v[240:243]
	s_mov_b32 m0, s11
	v_mfma_f32_16x16x32_bf16 v[244:247], v[184:187], v[224:227], v[244:247]
	global_load_lds_dwordx4 v[80:81], off
	v_lshl_add_u64 v[80:81], v[80:81], 0, s[34:35]
	v_mfma_f32_16x16x32_bf16 v[248:251], v[184:187], v[252:255], v[248:251]
	s_waitcnt vmcnt(6)
	s_barrier
	ds_read_b128 v[92:95], v84 offset:0
	ds_read_b128 v[100:103], v84 offset:2048
	ds_read_b128 v[148:151], v84 offset:4096
	ds_read_b128 v[180:183], v84 offset:6144
	ds_read_b128 v[188:191], v85 offset:32768
	ds_read_b128 v[212:215], v85 offset:34816
	ds_read_b128 v[220:223], v85 offset:36864
	ds_read_b128 v[228:231], v85 offset:38912
	ds_read_b128 v[96:99], v86 offset:0
	ds_read_b128 v[144:147], v86 offset:2048
	ds_read_b128 v[152:155], v86 offset:4096
	ds_read_b128 v[184:187], v86 offset:6144
	ds_read_b128 v[192:195], v87 offset:32768
	ds_read_b128 v[216:219], v87 offset:34816
	ds_read_b128 v[224:227], v87 offset:36864
	ds_read_b128 v[252:255], v87 offset:38912
	s_waitcnt lgkmcnt(0)
	s_barrier
	v_mfma_f32_16x16x32_bf16 v[2:5], v[92:95], v[188:191], v[2:5]
	v_mfma_f32_16x16x32_bf16 v[6:9], v[92:95], v[212:215], v[6:9]
	s_mov_b32 m0, s1
	v_mfma_f32_16x16x32_bf16 v[10:13], v[92:95], v[220:223], v[10:13]
	global_load_lds_dwordx4 v[66:67], off
	v_mfma_f32_16x16x32_bf16 v[14:17], v[92:95], v[228:231], v[14:17]
	v_mfma_f32_16x16x32_bf16 v[18:21], v[100:103], v[188:191], v[18:21]
	v_mfma_f32_16x16x32_bf16 v[22:25], v[100:103], v[212:215], v[22:25]
	v_mfma_f32_16x16x32_bf16 v[26:29], v[100:103], v[220:223], v[26:29]
	v_mfma_f32_16x16x32_bf16 v[30:33], v[100:103], v[228:231], v[30:33]
	s_add_i32 m0, s1, 0x400
	v_mfma_f32_16x16x32_bf16 v[34:37], v[148:151], v[188:191], v[34:37]
	global_load_lds_dwordx4 v[70:71], off
	v_mfma_f32_16x16x32_bf16 v[38:41], v[148:151], v[212:215], v[38:41]
	v_mfma_f32_16x16x32_bf16 v[42:45], v[148:151], v[220:223], v[42:45]
	v_mfma_f32_16x16x32_bf16 v[46:49], v[148:151], v[228:231], v[46:49]
	v_mfma_f32_16x16x32_bf16 v[50:53], v[180:183], v[188:191], v[50:53]
	v_mfma_f32_16x16x32_bf16 v[54:57], v[180:183], v[212:215], v[54:57]
	s_add_i32 m0, s1, 0x800
	v_mfma_f32_16x16x32_bf16 v[58:61], v[180:183], v[220:223], v[58:61]
	global_load_lds_dwordx4 v[74:75], off
	v_mfma_f32_16x16x32_bf16 v[62:65], v[180:183], v[228:231], v[62:65]
	v_mfma_f32_16x16x32_bf16 v[2:5], v[96:99], v[192:195], v[2:5]
	v_mfma_f32_16x16x32_bf16 v[6:9], v[96:99], v[216:219], v[6:9]
	s_add_i32 m0, s1, 0xc00
	v_mfma_f32_16x16x32_bf16 v[10:13], v[96:99], v[224:227], v[10:13]
	global_load_lds_dwordx4 v[78:79], off
	v_mfma_f32_16x16x32_bf16 v[14:17], v[96:99], v[252:255], v[14:17]
	v_mfma_f32_16x16x32_bf16 v[18:21], v[144:147], v[192:195], v[18:21]
	v_mfma_f32_16x16x32_bf16 v[22:25], v[144:147], v[216:219], v[22:25]
	v_mfma_f32_16x16x32_bf16 v[26:29], v[144:147], v[224:227], v[26:29]
	v_mfma_f32_16x16x32_bf16 v[30:33], v[144:147], v[252:255], v[30:33]
	s_mov_b32 m0, s7
	v_mfma_f32_16x16x32_bf16 v[34:37], v[152:155], v[192:195], v[34:37]
	global_load_lds_dwordx4 v[68:69], off
	v_lshl_add_u64 v[68:69], v[68:69], 0, s[34:35]
	v_mfma_f32_16x16x32_bf16 v[38:41], v[152:155], v[216:219], v[38:41]
	v_mfma_f32_16x16x32_bf16 v[42:45], v[152:155], v[224:227], v[42:45]
	v_mfma_f32_16x16x32_bf16 v[46:49], v[152:155], v[252:255], v[46:49]
	v_mfma_f32_16x16x32_bf16 v[50:53], v[184:187], v[192:195], v[50:53]
	v_mfma_f32_16x16x32_bf16 v[54:57], v[184:187], v[216:219], v[54:57]
	s_mov_b32 m0, s14
	v_mfma_f32_16x16x32_bf16 v[58:61], v[184:187], v[224:227], v[58:61]
	global_load_lds_dwordx4 v[72:73], off
	v_lshl_add_u64 v[72:73], v[72:73], 0, s[34:35]
	v_mfma_f32_16x16x32_bf16 v[62:65], v[184:187], v[252:255], v[62:65]
	s_waitcnt vmcnt(6)
	s_barrier
	ds_read_b128 v[92:95], v84 offset:32768
	ds_read_b128 v[100:103], v84 offset:34816
	ds_read_b128 v[148:151], v84 offset:36864
	ds_read_b128 v[180:183], v84 offset:38912
	ds_read_b128 v[96:99], v86 offset:32768
	ds_read_b128 v[144:147], v86 offset:34816
	ds_read_b128 v[152:155], v86 offset:36864
	ds_read_b128 v[184:187], v86 offset:38912
	s_waitcnt lgkmcnt(0)
	s_barrier
	v_mfma_f32_16x16x32_bf16 v[104:107], v[92:95], v[188:191], v[104:107]
	v_mfma_f32_16x16x32_bf16 v[108:111], v[92:95], v[212:215], v[108:111]
	s_mov_b32 m0, s6
	v_lshl_add_u64 v[82:83], v[66:67], 0, s[26:27]
	v_mfma_f32_16x16x32_bf16 v[112:115], v[92:95], v[220:223], v[112:115]
	global_load_lds_dwordx4 v[82:83], off
	v_lshl_add_u64 v[66:67], v[66:67], 0, s[34:35]
	v_mfma_f32_16x16x32_bf16 v[116:119], v[92:95], v[228:231], v[116:119]
	v_mfma_f32_16x16x32_bf16 v[128:131], v[100:103], v[188:191], v[128:131]
	v_mfma_f32_16x16x32_bf16 v[132:135], v[100:103], v[212:215], v[132:135]
	v_mfma_f32_16x16x32_bf16 v[136:139], v[100:103], v[220:223], v[136:139]
	v_mfma_f32_16x16x32_bf16 v[140:143], v[100:103], v[228:231], v[140:143]
	s_mov_b32 m0, s13
	v_lshl_add_u64 v[82:83], v[70:71], 0, s[26:27]
	v_mfma_f32_16x16x32_bf16 v[196:199], v[148:151], v[188:191], v[196:199]
	global_load_lds_dwordx4 v[82:83], off
	v_lshl_add_u64 v[70:71], v[70:71], 0, s[34:35]
	v_mfma_f32_16x16x32_bf16 v[200:203], v[148:151], v[212:215], v[200:203]
	v_mfma_f32_16x16x32_bf16 v[204:207], v[148:151], v[220:223], v[204:207]
	v_mfma_f32_16x16x32_bf16 v[208:211], v[148:151], v[228:231], v[208:211]
	v_mfma_f32_16x16x32_bf16 v[236:239], v[180:183], v[188:191], v[236:239]
	v_mfma_f32_16x16x32_bf16 v[240:243], v[180:183], v[212:215], v[240:243]
	s_mov_b32 m0, s15
	v_lshl_add_u64 v[82:83], v[74:75], 0, s[26:27]
	v_mfma_f32_16x16x32_bf16 v[244:247], v[180:183], v[220:223], v[244:247]
	global_load_lds_dwordx4 v[82:83], off
	v_lshl_add_u64 v[74:75], v[74:75], 0, s[34:35]
	v_mfma_f32_16x16x32_bf16 v[248:251], v[180:183], v[228:231], v[248:251]
	v_mfma_f32_16x16x32_bf16 v[104:107], v[96:99], v[192:195], v[104:107]
	v_mfma_f32_16x16x32_bf16 v[108:111], v[96:99], v[216:219], v[108:111]
	s_mov_b32 m0, s17
	v_lshl_add_u64 v[82:83], v[78:79], 0, s[26:27]
	v_mfma_f32_16x16x32_bf16 v[112:115], v[96:99], v[224:227], v[112:115]
	global_load_lds_dwordx4 v[82:83], off
	v_lshl_add_u64 v[78:79], v[78:79], 0, s[34:35]
	v_mfma_f32_16x16x32_bf16 v[116:119], v[96:99], v[252:255], v[116:119]
	v_mfma_f32_16x16x32_bf16 v[128:131], v[144:147], v[192:195], v[128:131]
	v_mfma_f32_16x16x32_bf16 v[132:135], v[144:147], v[216:219], v[132:135]
	v_mfma_f32_16x16x32_bf16 v[136:139], v[144:147], v[224:227], v[136:139]
	v_mfma_f32_16x16x32_bf16 v[140:143], v[144:147], v[252:255], v[140:143]
	s_mov_b32 m0, s16
	v_mfma_f32_16x16x32_bf16 v[196:199], v[152:155], v[192:195], v[196:199]
	global_load_lds_dwordx4 v[76:77], off
	v_lshl_add_u64 v[76:77], v[76:77], 0, s[34:35]
	v_mfma_f32_16x16x32_bf16 v[200:203], v[152:155], v[216:219], v[200:203]
	v_mfma_f32_16x16x32_bf16 v[204:207], v[152:155], v[224:227], v[204:207]
	v_mfma_f32_16x16x32_bf16 v[208:211], v[152:155], v[252:255], v[208:211]
	v_mfma_f32_16x16x32_bf16 v[236:239], v[184:187], v[192:195], v[236:239]
	v_mfma_f32_16x16x32_bf16 v[240:243], v[184:187], v[216:219], v[240:243]
	s_mov_b32 m0, s25
	v_mfma_f32_16x16x32_bf16 v[244:247], v[184:187], v[224:227], v[244:247]
	global_load_lds_dwordx4 v[80:81], off
	v_lshl_add_u64 v[80:81], v[80:81], 0, s[34:35]
	v_mfma_f32_16x16x32_bf16 v[248:251], v[184:187], v[252:255], v[248:251]
	s_waitcnt vmcnt(6)
	s_barrier
	s_add_i32 s12, s12, 2
	s_cmp_lt_u32 s12, 14
	s_cbranch_scc1 .Lg1_loop_w2
	ds_read_b128 v[92:95], v84 offset:0
	ds_read_b128 v[100:103], v84 offset:2048
	ds_read_b128 v[148:151], v84 offset:4096
	ds_read_b128 v[180:183], v84 offset:6144
	ds_read_b128 v[188:191], v85 offset:0
	ds_read_b128 v[212:215], v85 offset:2048
	ds_read_b128 v[220:223], v85 offset:4096
	ds_read_b128 v[228:231], v85 offset:6144
	ds_read_b128 v[96:99], v86 offset:0
	ds_read_b128 v[144:147], v86 offset:2048
	ds_read_b128 v[152:155], v86 offset:4096
	ds_read_b128 v[184:187], v86 offset:6144
	ds_read_b128 v[192:195], v87 offset:0
	ds_read_b128 v[216:219], v87 offset:2048
	ds_read_b128 v[224:227], v87 offset:4096
	ds_read_b128 v[252:255], v87 offset:6144
	s_waitcnt lgkmcnt(0)
	s_barrier
	v_mfma_f32_16x16x32_bf16 v[2:5], v[92:95], v[188:191], v[2:5]
	v_mfma_f32_16x16x32_bf16 v[6:9], v[92:95], v[212:215], v[6:9]
	s_mov_b32 m0, s1
	v_mfma_f32_16x16x32_bf16 v[10:13], v[92:95], v[220:223], v[10:13]
	global_load_lds_dwordx4 v[66:67], off
	v_mfma_f32_16x16x32_bf16 v[14:17], v[92:95], v[228:231], v[14:17]
	v_mfma_f32_16x16x32_bf16 v[18:21], v[100:103], v[188:191], v[18:21]
	v_mfma_f32_16x16x32_bf16 v[22:25], v[100:103], v[212:215], v[22:25]
	v_mfma_f32_16x16x32_bf16 v[26:29], v[100:103], v[220:223], v[26:29]
	v_mfma_f32_16x16x32_bf16 v[30:33], v[100:103], v[228:231], v[30:33]
	s_add_i32 m0, s1, 0x400
	v_mfma_f32_16x16x32_bf16 v[34:37], v[148:151], v[188:191], v[34:37]
	global_load_lds_dwordx4 v[70:71], off
	v_mfma_f32_16x16x32_bf16 v[38:41], v[148:151], v[212:215], v[38:41]
	v_mfma_f32_16x16x32_bf16 v[42:45], v[148:151], v[220:223], v[42:45]
	v_mfma_f32_16x16x32_bf16 v[46:49], v[148:151], v[228:231], v[46:49]
	v_mfma_f32_16x16x32_bf16 v[50:53], v[180:183], v[188:191], v[50:53]
	v_mfma_f32_16x16x32_bf16 v[54:57], v[180:183], v[212:215], v[54:57]
	v_mfma_f32_16x16x32_bf16 v[58:61], v[180:183], v[220:223], v[58:61]
	v_mfma_f32_16x16x32_bf16 v[62:65], v[180:183], v[228:231], v[62:65]
	v_mfma_f32_16x16x32_bf16 v[2:5], v[96:99], v[192:195], v[2:5]
	v_mfma_f32_16x16x32_bf16 v[6:9], v[96:99], v[216:219], v[6:9]
	s_add_i32 m0, s1, 0x800
	v_mfma_f32_16x16x32_bf16 v[10:13], v[96:99], v[224:227], v[10:13]
	global_load_lds_dwordx4 v[74:75], off
	v_mfma_f32_16x16x32_bf16 v[14:17], v[96:99], v[252:255], v[14:17]
	v_mfma_f32_16x16x32_bf16 v[18:21], v[144:147], v[192:195], v[18:21]
	v_mfma_f32_16x16x32_bf16 v[22:25], v[144:147], v[216:219], v[22:25]
	v_mfma_f32_16x16x32_bf16 v[26:29], v[144:147], v[224:227], v[26:29]
	v_mfma_f32_16x16x32_bf16 v[30:33], v[144:147], v[252:255], v[30:33]
	s_add_i32 m0, s1, 0xc00
	v_mfma_f32_16x16x32_bf16 v[34:37], v[152:155], v[192:195], v[34:37]
	global_load_lds_dwordx4 v[78:79], off
	v_mfma_f32_16x16x32_bf16 v[38:41], v[152:155], v[216:219], v[38:41]
	v_mfma_f32_16x16x32_bf16 v[42:45], v[152:155], v[224:227], v[42:45]
	v_mfma_f32_16x16x32_bf16 v[46:49], v[152:155], v[252:255], v[46:49]
	v_mfma_f32_16x16x32_bf16 v[50:53], v[184:187], v[192:195], v[50:53]
	v_mfma_f32_16x16x32_bf16 v[54:57], v[184:187], v[216:219], v[54:57]
	v_mfma_f32_16x16x32_bf16 v[58:61], v[184:187], v[224:227], v[58:61]
	v_mfma_f32_16x16x32_bf16 v[62:65], v[184:187], v[252:255], v[62:65]
	s_waitcnt vmcnt(4)
	s_barrier
	ds_read_b128 v[92:95], v84 offset:32768
	ds_read_b128 v[100:103], v84 offset:34816
	ds_read_b128 v[148:151], v84 offset:36864
	ds_read_b128 v[180:183], v84 offset:38912
	ds_read_b128 v[96:99], v86 offset:32768
	ds_read_b128 v[144:147], v86 offset:34816
	ds_read_b128 v[152:155], v86 offset:36864
	ds_read_b128 v[184:187], v86 offset:38912
	s_waitcnt lgkmcnt(0)
	s_barrier
	v_mfma_f32_16x16x32_bf16 v[104:107], v[92:95], v[188:191], v[104:107]
	v_mfma_f32_16x16x32_bf16 v[108:111], v[92:95], v[212:215], v[108:111]
	s_mov_b32 m0, s6
	v_lshl_add_u64 v[82:83], v[66:67], 0, s[26:27]
	v_mfma_f32_16x16x32_bf16 v[112:115], v[92:95], v[220:223], v[112:115]
	global_load_lds_dwordx4 v[82:83], off
	v_lshl_add_u64 v[66:67], v[66:67], 0, s[34:35]
	v_mfma_f32_16x16x32_bf16 v[116:119], v[92:95], v[228:231], v[116:119]
	v_mfma_f32_16x16x32_bf16 v[128:131], v[100:103], v[188:191], v[128:131]
	v_mfma_f32_16x16x32_bf16 v[132:135], v[100:103], v[212:215], v[132:135]
	v_mfma_f32_16x16x32_bf16 v[136:139], v[100:103], v[220:223], v[136:139]
	v_mfma_f32_16x16x32_bf16 v[140:143], v[100:103], v[228:231], v[140:143]
	s_mov_b32 m0, s13
	v_lshl_add_u64 v[82:83], v[70:71], 0, s[26:27]
	v_mfma_f32_16x16x32_bf16 v[196:199], v[148:151], v[188:191], v[196:199]
	global_load_lds_dwordx4 v[82:83], off
	v_lshl_add_u64 v[70:71], v[70:71], 0, s[34:35]
	v_mfma_f32_16x16x32_bf16 v[200:203], v[148:151], v[212:215], v[200:203]
	v_mfma_f32_16x16x32_bf16 v[204:207], v[148:151], v[220:223], v[204:207]
	v_mfma_f32_16x16x32_bf16 v[208:211], v[148:151], v[228:231], v[208:211]
	v_mfma_f32_16x16x32_bf16 v[236:239], v[180:183], v[188:191], v[236:239]
	v_mfma_f32_16x16x32_bf16 v[240:243], v[180:183], v[212:215], v[240:243]
	v_mfma_f32_16x16x32_bf16 v[244:247], v[180:183], v[220:223], v[244:247]
	v_mfma_f32_16x16x32_bf16 v[248:251], v[180:183], v[228:231], v[248:251]
	v_mfma_f32_16x16x32_bf16 v[104:107], v[96:99], v[192:195], v[104:107]
	v_mfma_f32_16x16x32_bf16 v[108:111], v[96:99], v[216:219], v[108:111]
	s_mov_b32 m0, s15
	v_lshl_add_u64 v[82:83], v[74:75], 0, s[26:27]
	v_mfma_f32_16x16x32_bf16 v[112:115], v[96:99], v[224:227], v[112:115]
	global_load_lds_dwordx4 v[82:83], off
	v_lshl_add_u64 v[74:75], v[74:75], 0, s[34:35]
	v_mfma_f32_16x16x32_bf16 v[116:119], v[96:99], v[252:255], v[116:119]
	v_mfma_f32_16x16x32_bf16 v[128:131], v[144:147], v[192:195], v[128:131]
	v_mfma_f32_16x16x32_bf16 v[132:135], v[144:147], v[216:219], v[132:135]
	v_mfma_f32_16x16x32_bf16 v[136:139], v[144:147], v[224:227], v[136:139]
	v_mfma_f32_16x16x32_bf16 v[140:143], v[144:147], v[252:255], v[140:143]
	s_mov_b32 m0, s17
	v_lshl_add_u64 v[82:83], v[78:79], 0, s[26:27]
	v_mfma_f32_16x16x32_bf16 v[196:199], v[152:155], v[192:195], v[196:199]
	global_load_lds_dwordx4 v[82:83], off
	v_lshl_add_u64 v[78:79], v[78:79], 0, s[34:35]
	v_mfma_f32_16x16x32_bf16 v[200:203], v[152:155], v[216:219], v[200:203]
	v_mfma_f32_16x16x32_bf16 v[204:207], v[152:155], v[224:227], v[204:207]
	v_mfma_f32_16x16x32_bf16 v[208:211], v[152:155], v[252:255], v[208:211]
	v_mfma_f32_16x16x32_bf16 v[236:239], v[184:187], v[192:195], v[236:239]
	v_mfma_f32_16x16x32_bf16 v[240:243], v[184:187], v[216:219], v[240:243]
	v_mfma_f32_16x16x32_bf16 v[244:247], v[184:187], v[224:227], v[244:247]
	v_mfma_f32_16x16x32_bf16 v[248:251], v[184:187], v[252:255], v[248:251]
	s_waitcnt vmcnt(4)
	s_barrier
	ds_read_b128 v[92:95], v84 offset:0
	ds_read_b128 v[100:103], v84 offset:2048
	ds_read_b128 v[148:151], v84 offset:4096
	ds_read_b128 v[180:183], v84 offset:6144
	ds_read_b128 v[188:191], v85 offset:32768
	ds_read_b128 v[212:215], v85 offset:34816
	ds_read_b128 v[220:223], v85 offset:36864
	ds_read_b128 v[228:231], v85 offset:38912
	ds_read_b128 v[96:99], v86 offset:0
	ds_read_b128 v[144:147], v86 offset:2048
	ds_read_b128 v[152:155], v86 offset:4096
	ds_read_b128 v[184:187], v86 offset:6144
	ds_read_b128 v[192:195], v87 offset:32768
	ds_read_b128 v[216:219], v87 offset:34816
	ds_read_b128 v[224:227], v87 offset:36864
	ds_read_b128 v[252:255], v87 offset:38912
	s_waitcnt lgkmcnt(0)
	s_barrier
	v_mfma_f32_16x16x32_bf16 v[2:5], v[92:95], v[188:191], v[2:5]
	v_mfma_f32_16x16x32_bf16 v[6:9], v[92:95], v[212:215], v[6:9]
	v_mfma_f32_16x16x32_bf16 v[10:13], v[92:95], v[220:223], v[10:13]
	v_mfma_f32_16x16x32_bf16 v[14:17], v[92:95], v[228:231], v[14:17]
	v_mfma_f32_16x16x32_bf16 v[18:21], v[100:103], v[188:191], v[18:21]
	v_mfma_f32_16x16x32_bf16 v[22:25], v[100:103], v[212:215], v[22:25]
	v_mfma_f32_16x16x32_bf16 v[26:29], v[100:103], v[220:223], v[26:29]
	v_mfma_f32_16x16x32_bf16 v[30:33], v[100:103], v[228:231], v[30:33]
	v_mfma_f32_16x16x32_bf16 v[34:37], v[148:151], v[188:191], v[34:37]
	v_mfma_f32_16x16x32_bf16 v[38:41], v[148:151], v[212:215], v[38:41]
	v_mfma_f32_16x16x32_bf16 v[42:45], v[148:151], v[220:223], v[42:45]
	v_mfma_f32_16x16x32_bf16 v[46:49], v[148:151], v[228:231], v[46:49]
	v_mfma_f32_16x16x32_bf16 v[50:53], v[180:183], v[188:191], v[50:53]
	v_mfma_f32_16x16x32_bf16 v[54:57], v[180:183], v[212:215], v[54:57]
	v_mfma_f32_16x16x32_bf16 v[58:61], v[180:183], v[220:223], v[58:61]
	v_mfma_f32_16x16x32_bf16 v[62:65], v[180:183], v[228:231], v[62:65]
	v_mfma_f32_16x16x32_bf16 v[2:5], v[96:99], v[192:195], v[2:5]
	v_mfma_f32_16x16x32_bf16 v[6:9], v[96:99], v[216:219], v[6:9]
	v_mfma_f32_16x16x32_bf16 v[10:13], v[96:99], v[224:227], v[10:13]
	v_mfma_f32_16x16x32_bf16 v[14:17], v[96:99], v[252:255], v[14:17]
	v_mfma_f32_16x16x32_bf16 v[18:21], v[144:147], v[192:195], v[18:21]
	v_mfma_f32_16x16x32_bf16 v[22:25], v[144:147], v[216:219], v[22:25]
	v_mfma_f32_16x16x32_bf16 v[26:29], v[144:147], v[224:227], v[26:29]
	v_mfma_f32_16x16x32_bf16 v[30:33], v[144:147], v[252:255], v[30:33]
	v_mfma_f32_16x16x32_bf16 v[34:37], v[152:155], v[192:195], v[34:37]
	v_mfma_f32_16x16x32_bf16 v[38:41], v[152:155], v[216:219], v[38:41]
	v_mfma_f32_16x16x32_bf16 v[42:45], v[152:155], v[224:227], v[42:45]
	v_mfma_f32_16x16x32_bf16 v[46:49], v[152:155], v[252:255], v[46:49]
	v_mfma_f32_16x16x32_bf16 v[50:53], v[184:187], v[192:195], v[50:53]
	v_mfma_f32_16x16x32_bf16 v[54:57], v[184:187], v[216:219], v[54:57]
	v_mfma_f32_16x16x32_bf16 v[58:61], v[184:187], v[224:227], v[58:61]
	v_mfma_f32_16x16x32_bf16 v[62:65], v[184:187], v[252:255], v[62:65]
	s_waitcnt vmcnt(0)
	s_barrier
	ds_read_b128 v[92:95], v84 offset:32768
	ds_read_b128 v[100:103], v84 offset:34816
	ds_read_b128 v[148:151], v84 offset:36864
	ds_read_b128 v[180:183], v84 offset:38912
	ds_read_b128 v[96:99], v86 offset:32768
	ds_read_b128 v[144:147], v86 offset:34816
	ds_read_b128 v[152:155], v86 offset:36864
	ds_read_b128 v[184:187], v86 offset:38912
	s_waitcnt lgkmcnt(0)
	s_barrier
	v_mfma_f32_16x16x32_bf16 v[104:107], v[92:95], v[188:191], v[104:107]
	v_mfma_f32_16x16x32_bf16 v[108:111], v[92:95], v[212:215], v[108:111]
	v_mfma_f32_16x16x32_bf16 v[112:115], v[92:95], v[220:223], v[112:115]
	v_mfma_f32_16x16x32_bf16 v[116:119], v[92:95], v[228:231], v[116:119]
	v_mfma_f32_16x16x32_bf16 v[128:131], v[100:103], v[188:191], v[128:131]
	v_mfma_f32_16x16x32_bf16 v[132:135], v[100:103], v[212:215], v[132:135]
	v_mfma_f32_16x16x32_bf16 v[136:139], v[100:103], v[220:223], v[136:139]
	v_mfma_f32_16x16x32_bf16 v[140:143], v[100:103], v[228:231], v[140:143]
	v_mfma_f32_16x16x32_bf16 v[196:199], v[148:151], v[188:191], v[196:199]
	v_mfma_f32_16x16x32_bf16 v[200:203], v[148:151], v[212:215], v[200:203]
	v_mfma_f32_16x16x32_bf16 v[204:207], v[148:151], v[220:223], v[204:207]
	v_mfma_f32_16x16x32_bf16 v[208:211], v[148:151], v[228:231], v[208:211]
	v_mfma_f32_16x16x32_bf16 v[236:239], v[180:183], v[188:191], v[236:239]
	v_mfma_f32_16x16x32_bf16 v[240:243], v[180:183], v[212:215], v[240:243]
	v_mfma_f32_16x16x32_bf16 v[244:247], v[180:183], v[220:223], v[244:247]
	v_mfma_f32_16x16x32_bf16 v[248:251], v[180:183], v[228:231], v[248:251]
	v_mfma_f32_16x16x32_bf16 v[104:107], v[96:99], v[192:195], v[104:107]
	v_mfma_f32_16x16x32_bf16 v[108:111], v[96:99], v[216:219], v[108:111]
	v_mfma_f32_16x16x32_bf16 v[112:115], v[96:99], v[224:227], v[112:115]
	v_mfma_f32_16x16x32_bf16 v[116:119], v[96:99], v[252:255], v[116:119]
	v_mfma_f32_16x16x32_bf16 v[128:131], v[144:147], v[192:195], v[128:131]
	v_mfma_f32_16x16x32_bf16 v[132:135], v[144:147], v[216:219], v[132:135]
	v_mfma_f32_16x16x32_bf16 v[136:139], v[144:147], v[224:227], v[136:139]
	v_mfma_f32_16x16x32_bf16 v[140:143], v[144:147], v[252:255], v[140:143]
	v_mfma_f32_16x16x32_bf16 v[196:199], v[152:155], v[192:195], v[196:199]
	v_mfma_f32_16x16x32_bf16 v[200:203], v[152:155], v[216:219], v[200:203]
	v_mfma_f32_16x16x32_bf16 v[204:207], v[152:155], v[224:227], v[204:207]
	v_mfma_f32_16x16x32_bf16 v[208:211], v[152:155], v[252:255], v[208:211]
	v_mfma_f32_16x16x32_bf16 v[236:239], v[184:187], v[192:195], v[236:239]
	v_mfma_f32_16x16x32_bf16 v[240:243], v[184:187], v[216:219], v[240:243]
	v_mfma_f32_16x16x32_bf16 v[244:247], v[184:187], v[224:227], v[244:247]
	v_mfma_f32_16x16x32_bf16 v[248:251], v[184:187], v[252:255], v[248:251]
	s_waitcnt vmcnt(0) lgkmcnt(0)
	s_barrier
	s_branch .Lm16_conv
.Lg1_loop_w3:
	ds_read_b128 v[92:95], v84 offset:0
	ds_read_b128 v[100:103], v84 offset:2048
	ds_read_b128 v[148:151], v84 offset:4096
	ds_read_b128 v[180:183], v84 offset:6144
	ds_read_b128 v[188:191], v85 offset:0
	ds_read_b128 v[212:215], v85 offset:2048
	ds_read_b128 v[220:223], v85 offset:4096
	ds_read_b128 v[228:231], v85 offset:6144
	ds_read_b128 v[96:99], v86 offset:0
	ds_read_b128 v[144:147], v86 offset:2048
	ds_read_b128 v[152:155], v86 offset:4096
	ds_read_b128 v[184:187], v86 offset:6144
	ds_read_b128 v[192:195], v87 offset:0
	ds_read_b128 v[216:219], v87 offset:2048
	ds_read_b128 v[224:227], v87 offset:4096
	ds_read_b128 v[252:255], v87 offset:6144
	s_waitcnt lgkmcnt(0)
	s_barrier
	v_mfma_f32_16x16x32_bf16 v[2:5], v[92:95], v[188:191], v[2:5]
	v_mfma_f32_16x16x32_bf16 v[6:9], v[92:95], v[212:215], v[6:9]
	v_mfma_f32_16x16x32_bf16 v[10:13], v[92:95], v[220:223], v[10:13]
	v_mfma_f32_16x16x32_bf16 v[14:17], v[92:95], v[228:231], v[14:17]
	s_mov_b32 m0, s1
	v_mfma_f32_16x16x32_bf16 v[18:21], v[100:103], v[188:191], v[18:21]
	global_load_lds_dwordx4 v[66:67], off
	v_mfma_f32_16x16x32_bf16 v[22:25], v[100:103], v[212:215], v[22:25]
	v_mfma_f32_16x16x32_bf16 v[26:29], v[100:103], v[220:223], v[26:29]
	v_mfma_f32_16x16x32_bf16 v[30:33], v[100:103], v[228:231], v[30:33]
	v_mfma_f32_16x16x32_bf16 v[34:37], v[148:151], v[188:191], v[34:37]
	v_mfma_f32_16x16x32_bf16 v[38:41], v[148:151], v[212:215], v[38:41]
	s_add_i32 m0, s1, 0x400
	v_mfma_f32_16x16x32_bf16 v[42:45], v[148:151], v[220:223], v[42:45]
	global_load_lds_dwordx4 v[70:71], off
	v_mfma_f32_16x16x32_bf16 v[46:49], v[148:151], v[228:231], v[46:49]
	v_mfma_f32_16x16x32_bf16 v[50:53], v[180:183], v[188:191], v[50:53]
	v_mfma_f32_16x16x32_bf16 v[54:57], v[180:183], v[212:215], v[54:57]
	s_add_i32 m0, s1, 0x800
	v_mfma_f32_16x16x32_bf16 v[58:61], v[180:183], v[220:223], v[58:61]
	global_load_lds_dwordx4 v[74:75], off
	v_mfma_f32_16x16x32_bf16 v[62:65], v[180:183], v[228:231], v[62:65]
	v_mfma_f32_16x16x32_bf16 v[2:5], v[96:99], v[192:195], v[2:5]
	v_mfma_f32_16x16x32_bf16 v[6:9], v[96:99], v[216:219], v[6:9]
	v_mfma_f32_16x16x32_bf16 v[10:13], v[96:99], v[224:227], v[10:13]
	v_mfma_f32_16x16x32_bf16 v[14:17], v[96:99], v[252:255], v[14:17]
	s_add_i32 m0, s1, 0xc00
	v_mfma_f32_16x16x32_bf16 v[18:21], v[144:147], v[192:195], v[18:21]
	global_load_lds_dwordx4 v[78:79], off
	v_mfma_f32_16x16x32_bf16 v[22:25], v[144:147], v[216:219], v[22:25]
	v_mfma_f32_16x16x32_bf16 v[26:29], v[144:147], v[224:227], v[26:29]
	v_mfma_f32_16x16x32_bf16 v[30:33], v[144:147], v[252:255], v[30:33]
	v_mfma_f32_16x16x32_bf16 v[34:37], v[152:155], v[192:195], v[34:37]
	v_mfma_f32_16x16x32_bf16 v[38:41], v[152:155], v[216:219], v[38:41]
	s_mov_b32 m0, s8
	v_mfma_f32_16x16x32_bf16 v[42:45], v[152:155], v[224:227], v[42:45]
	global_load_lds_dwordx4 v[68:69], off
	v_lshl_add_u64 v[68:69], v[68:69], 0, s[34:35]
	v_mfma_f32_16x16x32_bf16 v[46:49], v[152:155], v[252:255], v[46:49]
	v_mfma_f32_16x16x32_bf16 v[50:53], v[184:187], v[192:195], v[50:53]
	v_mfma_f32_16x16x32_bf16 v[54:57], v[184:187], v[216:219], v[54:57]
	s_mov_b32 m0, s9
	v_mfma_f32_16x16x32_bf16 v[58:61], v[184:187], v[224:227], v[58:61]
	global_load_lds_dwordx4 v[72:73], off
	v_lshl_add_u64 v[72:73], v[72:73], 0, s[34:35]
	v_mfma_f32_16x16x32_bf16 v[62:65], v[184:187], v[252:255], v[62:65]
	s_waitcnt vmcnt(6)
	s_barrier
	ds_read_b128 v[92:95], v84 offset:32768
	ds_read_b128 v[100:103], v84 offset:34816
	ds_read_b128 v[148:151], v84 offset:36864
	ds_read_b128 v[180:183], v84 offset:38912
	ds_read_b128 v[96:99], v86 offset:32768
	ds_read_b128 v[144:147], v86 offset:34816
	ds_read_b128 v[152:155], v86 offset:36864
	ds_read_b128 v[184:187], v86 offset:38912
	s_waitcnt lgkmcnt(0)
	s_barrier
	v_mfma_f32_16x16x32_bf16 v[104:107], v[92:95], v[188:191], v[104:107]
	v_mfma_f32_16x16x32_bf16 v[108:111], v[92:95], v[212:215], v[108:111]
	v_mfma_f32_16x16x32_bf16 v[112:115], v[92:95], v[220:223], v[112:115]
	v_mfma_f32_16x16x32_bf16 v[116:119], v[92:95], v[228:231], v[116:119]
	s_mov_b32 m0, s6
	v_lshl_add_u64 v[82:83], v[66:67], 0, s[26:27]
	v_mfma_f32_16x16x32_bf16 v[128:131], v[100:103], v[188:191], v[128:131]
	global_load_lds_dwordx4 v[82:83], off
	v_lshl_add_u64 v[66:67], v[66:67], 0, s[34:35]
	v_mfma_f32_16x16x32_bf16 v[132:135], v[100:103], v[212:215], v[132:135]
	v_mfma_f32_16x16x32_bf16 v[136:139], v[100:103], v[220:223], v[136:139]
	v_mfma_f32_16x16x32_bf16 v[140:143], v[100:103], v[228:231], v[140:143]
	v_mfma_f32_16x16x32_bf16 v[196:199], v[148:151], v[188:191], v[196:199]
	v_mfma_f32_16x16x32_bf16 v[200:203], v[148:151], v[212:215], v[200:203]
	s_mov_b32 m0, s13
	v_lshl_add_u64 v[82:83], v[70:71], 0, s[26:27]
	v_mfma_f32_16x16x32_bf16 v[204:207], v[148:151], v[220:223], v[204:207]
	global_load_lds_dwordx4 v[82:83], off
	v_lshl_add_u64 v[70:71], v[70:71], 0, s[34:35]
	v_mfma_f32_16x16x32_bf16 v[208:211], v[148:151], v[228:231], v[208:211]
	v_mfma_f32_16x16x32_bf16 v[236:239], v[180:183], v[188:191], v[236:239]
	v_mfma_f32_16x16x32_bf16 v[240:243], v[180:183], v[212:215], v[240:243]
	s_mov_b32 m0, s15
	v_lshl_add_u64 v[82:83], v[74:75], 0, s[26:27]
	v_mfma_f32_16x16x32_bf16 v[244:247], v[180:183], v[220:223], v[244:247]
	global_load_lds_dwordx4 v[82:83], off
	v_lshl_add_u64 v[74:75], v[74:75], 0, s[34:35]
	v_mfma_f32_16x16x32_bf16 v[248:251], v[180:183], v[228:231], v[248:251]
	v_mfma_f32_16x16x32_bf16 v[104:107], v[96:99], v[192:195], v[104:107]
	v_mfma_f32_16x16x32_bf16 v[108:111], v[96:99], v[216:219], v[108:111]
	v_mfma_f32_16x16x32_bf16 v[112:115], v[96:99], v[224:227], v[112:115]
	v_mfma_f32_16x16x32_bf16 v[116:119], v[96:99], v[252:255], v[116:119]
	s_mov_b32 m0, s17
	v_lshl_add_u64 v[82:83], v[78:79], 0, s[26:27]
	v_mfma_f32_16x16x32_bf16 v[128:131], v[144:147], v[192:195], v[128:131]
	global_load_lds_dwordx4 v[82:83], off
	v_lshl_add_u64 v[78:79], v[78:79], 0, s[34:35]
	v_mfma_f32_16x16x32_bf16 v[132:135], v[144:147], v[216:219], v[132:135]
	v_mfma_f32_16x16x32_bf16 v[136:139], v[144:147], v[224:227], v[136:139]
	v_mfma_f32_16x16x32_bf16 v[140:143], v[144:147], v[252:255], v[140:143]
	v_mfma_f32_16x16x32_bf16 v[196:199], v[152:155], v[192:195], v[196:199]
	v_mfma_f32_16x16x32_bf16 v[200:203], v[152:155], v[216:219], v[200:203]
	s_mov_b32 m0, s10
	v_mfma_f32_16x16x32_bf16 v[204:207], v[152:155], v[224:227], v[204:207]
	global_load_lds_dwordx4 v[76:77], off
	v_lshl_add_u64 v[76:77], v[76:77], 0, s[34:35]
	v_mfma_f32_16x16x32_bf16 v[208:211], v[152:155], v[252:255], v[208:211]
	v_mfma_f32_16x16x32_bf16 v[236:239], v[184:187], v[192:195], v[236:239]
	v_mfma_f32_16x16x32_bf16 v[240:243], v[184:187], v[216:219], v[240:243]
	s_mov_b32 m0, s11
	v_mfma_f32_16x16x32_bf16 v[244:247], v[184:187], v[224:227], v[244:247]
	global_load_lds_dwordx4 v[80:81], off
	v_lshl_add_u64 v[80:81], v[80:81], 0, s[34:35]
	v_mfma_f32_16x16x32_bf16 v[248:251], v[184:187], v[252:255], v[248:251]
	s_waitcnt vmcnt(6)
	s_barrier
	ds_read_b128 v[92:95], v84 offset:0
	ds_read_b128 v[100:103], v84 offset:2048
	ds_read_b128 v[148:151], v84 offset:4096
	ds_read_b128 v[180:183], v84 offset:6144
	ds_read_b128 v[188:191], v85 offset:32768
	ds_read_b128 v[212:215], v85 offset:34816
	ds_read_b128 v[220:223], v85 offset:36864
	ds_read_b128 v[228:231], v85 offset:38912
	ds_read_b128 v[96:99], v86 offset:0
	ds_read_b128 v[144:147], v86 offset:2048
	ds_read_b128 v[152:155], v86 offset:4096
	ds_read_b128 v[184:187], v86 offset:6144
	ds_read_b128 v[192:195], v87 offset:32768
	ds_read_b128 v[216:219], v87 offset:34816
	ds_read_b128 v[224:227], v87 offset:36864
	ds_read_b128 v[252:255], v87 offset:38912
	s_waitcnt lgkmcnt(0)
	s_barrier
	v_mfma_f32_16x16x32_bf16 v[2:5], v[92:95], v[188:191], v[2:5]
	v_mfma_f32_16x16x32_bf16 v[6:9], v[92:95], v[212:215], v[6:9]
	v_mfma_f32_16x16x32_bf16 v[10:13], v[92:95], v[220:223], v[10:13]
	v_mfma_f32_16x16x32_bf16 v[14:17], v[92:95], v[228:231], v[14:17]
	s_mov_b32 m0, s1
	v_mfma_f32_16x16x32_bf16 v[18:21], v[100:103], v[188:191], v[18:21]
	global_load_lds_dwordx4 v[66:67], off
	v_mfma_f32_16x16x32_bf16 v[22:25], v[100:103], v[212:215], v[22:25]
	v_mfma_f32_16x16x32_bf16 v[26:29], v[100:103], v[220:223], v[26:29]
	v_mfma_f32_16x16x32_bf16 v[30:33], v[100:103], v[228:231], v[30:33]
	v_mfma_f32_16x16x32_bf16 v[34:37], v[148:151], v[188:191], v[34:37]
	v_mfma_f32_16x16x32_bf16 v[38:41], v[148:151], v[212:215], v[38:41]
	s_add_i32 m0, s1, 0x400
	v_mfma_f32_16x16x32_bf16 v[42:45], v[148:151], v[220:223], v[42:45]
	global_load_lds_dwordx4 v[70:71], off
	v_mfma_f32_16x16x32_bf16 v[46:49], v[148:151], v[228:231], v[46:49]
	v_mfma_f32_16x16x32_bf16 v[50:53], v[180:183], v[188:191], v[50:53]
	v_mfma_f32_16x16x32_bf16 v[54:57], v[180:183], v[212:215], v[54:57]
	s_add_i32 m0, s1, 0x800
	v_mfma_f32_16x16x32_bf16 v[58:61], v[180:183], v[220:223], v[58:61]
	global_load_lds_dwordx4 v[74:75], off
	v_mfma_f32_16x16x32_bf16 v[62:65], v[180:183], v[228:231], v[62:65]
	v_mfma_f32_16x16x32_bf16 v[2:5], v[96:99], v[192:195], v[2:5]
	v_mfma_f32_16x16x32_bf16 v[6:9], v[96:99], v[216:219], v[6:9]
	v_mfma_f32_16x16x32_bf16 v[10:13], v[96:99], v[224:227], v[10:13]
	v_mfma_f32_16x16x32_bf16 v[14:17], v[96:99], v[252:255], v[14:17]
	s_add_i32 m0, s1, 0xc00
	v_mfma_f32_16x16x32_bf16 v[18:21], v[144:147], v[192:195], v[18:21]
	global_load_lds_dwordx4 v[78:79], off
	v_mfma_f32_16x16x32_bf16 v[22:25], v[144:147], v[216:219], v[22:25]
	v_mfma_f32_16x16x32_bf16 v[26:29], v[144:147], v[224:227], v[26:29]
	v_mfma_f32_16x16x32_bf16 v[30:33], v[144:147], v[252:255], v[30:33]
	v_mfma_f32_16x16x32_bf16 v[34:37], v[152:155], v[192:195], v[34:37]
	v_mfma_f32_16x16x32_bf16 v[38:41], v[152:155], v[216:219], v[38:41]
	s_mov_b32 m0, s7
	v_mfma_f32_16x16x32_bf16 v[42:45], v[152:155], v[224:227], v[42:45]
	global_load_lds_dwordx4 v[68:69], off
	v_lshl_add_u64 v[68:69], v[68:69], 0, s[34:35]
	v_mfma_f32_16x16x32_bf16 v[46:49], v[152:155], v[252:255], v[46:49]
	v_mfma_f32_16x16x32_bf16 v[50:53], v[184:187], v[192:195], v[50:53]
	v_mfma_f32_16x16x32_bf16 v[54:57], v[184:187], v[216:219], v[54:57]
	s_mov_b32 m0, s14
	v_mfma_f32_16x16x32_bf16 v[58:61], v[184:187], v[224:227], v[58:61]
	global_load_lds_dwordx4 v[72:73], off
	v_lshl_add_u64 v[72:73], v[72:73], 0, s[34:35]
	v_mfma_f32_16x16x32_bf16 v[62:65], v[184:187], v[252:255], v[62:65]
	s_waitcnt vmcnt(6)
	s_barrier
	ds_read_b128 v[92:95], v84 offset:32768
	ds_read_b128 v[100:103], v84 offset:34816
	ds_read_b128 v[148:151], v84 offset:36864
	ds_read_b128 v[180:183], v84 offset:38912
	ds_read_b128 v[96:99], v86 offset:32768
	ds_read_b128 v[144:147], v86 offset:34816
	ds_read_b128 v[152:155], v86 offset:36864
	ds_read_b128 v[184:187], v86 offset:38912
	s_waitcnt lgkmcnt(0)
	s_barrier
	v_mfma_f32_16x16x32_bf16 v[104:107], v[92:95], v[188:191], v[104:107]
	v_mfma_f32_16x16x32_bf16 v[108:111], v[92:95], v[212:215], v[108:111]
	v_mfma_f32_16x16x32_bf16 v[112:115], v[92:95], v[220:223], v[112:115]
	v_mfma_f32_16x16x32_bf16 v[116:119], v[92:95], v[228:231], v[116:119]
	s_mov_b32 m0, s6
	v_lshl_add_u64 v[82:83], v[66:67], 0, s[26:27]
	v_mfma_f32_16x16x32_bf16 v[128:131], v[100:103], v[188:191], v[128:131]
	global_load_lds_dwordx4 v[82:83], off
	v_lshl_add_u64 v[66:67], v[66:67], 0, s[34:35]
	v_mfma_f32_16x16x32_bf16 v[132:135], v[100:103], v[212:215], v[132:135]
	v_mfma_f32_16x16x32_bf16 v[136:139], v[100:103], v[220:223], v[136:139]
	v_mfma_f32_16x16x32_bf16 v[140:143], v[100:103], v[228:231], v[140:143]
	v_mfma_f32_16x16x32_bf16 v[196:199], v[148:151], v[188:191], v[196:199]
	v_mfma_f32_16x16x32_bf16 v[200:203], v[148:151], v[212:215], v[200:203]
	s_mov_b32 m0, s13
	v_lshl_add_u64 v[82:83], v[70:71], 0, s[26:27]
	v_mfma_f32_16x16x32_bf16 v[204:207], v[148:151], v[220:223], v[204:207]
	global_load_lds_dwordx4 v[82:83], off
	v_lshl_add_u64 v[70:71], v[70:71], 0, s[34:35]
	v_mfma_f32_16x16x32_bf16 v[208:211], v[148:151], v[228:231], v[208:211]
	v_mfma_f32_16x16x32_bf16 v[236:239], v[180:183], v[188:191], v[236:239]
	v_mfma_f32_16x16x32_bf16 v[240:243], v[180:183], v[212:215], v[240:243]
	s_mov_b32 m0, s15
	v_lshl_add_u64 v[82:83], v[74:75], 0, s[26:27]
	v_mfma_f32_16x16x32_bf16 v[244:247], v[180:183], v[220:223], v[244:247]
	global_load_lds_dwordx4 v[82:83], off
	v_lshl_add_u64 v[74:75], v[74:75], 0, s[34:35]
	v_mfma_f32_16x16x32_bf16 v[248:251], v[180:183], v[228:231], v[248:251]
	v_mfma_f32_16x16x32_bf16 v[104:107], v[96:99], v[192:195], v[104:107]
	v_mfma_f32_16x16x32_bf16 v[108:111], v[96:99], v[216:219], v[108:111]
	v_mfma_f32_16x16x32_bf16 v[112:115], v[96:99], v[224:227], v[112:115]
	v_mfma_f32_16x16x32_bf16 v[116:119], v[96:99], v[252:255], v[116:119]
	s_mov_b32 m0, s17
	v_lshl_add_u64 v[82:83], v[78:79], 0, s[26:27]
	v_mfma_f32_16x16x32_bf16 v[128:131], v[144:147], v[192:195], v[128:131]
	global_load_lds_dwordx4 v[82:83], off
	v_lshl_add_u64 v[78:79], v[78:79], 0, s[34:35]
	v_mfma_f32_16x16x32_bf16 v[132:135], v[144:147], v[216:219], v[132:135]
	v_mfma_f32_16x16x32_bf16 v[136:139], v[144:147], v[224:227], v[136:139]
	v_mfma_f32_16x16x32_bf16 v[140:143], v[144:147], v[252:255], v[140:143]
	v_mfma_f32_16x16x32_bf16 v[196:199], v[152:155], v[192:195], v[196:199]
	v_mfma_f32_16x16x32_bf16 v[200:203], v[152:155], v[216:219], v[200:203]
	s_mov_b32 m0, s16
	v_mfma_f32_16x16x32_bf16 v[204:207], v[152:155], v[224:227], v[204:207]
	global_load_lds_dwordx4 v[76:77], off
	v_lshl_add_u64 v[76:77], v[76:77], 0, s[34:35]
	v_mfma_f32_16x16x32_bf16 v[208:211], v[152:155], v[252:255], v[208:211]
	v_mfma_f32_16x16x32_bf16 v[236:239], v[184:187], v[192:195], v[236:239]
	v_mfma_f32_16x16x32_bf16 v[240:243], v[184:187], v[216:219], v[240:243]
	s_mov_b32 m0, s25
	v_mfma_f32_16x16x32_bf16 v[244:247], v[184:187], v[224:227], v[244:247]
	global_load_lds_dwordx4 v[80:81], off
	v_lshl_add_u64 v[80:81], v[80:81], 0, s[34:35]
	v_mfma_f32_16x16x32_bf16 v[248:251], v[184:187], v[252:255], v[248:251]
	s_waitcnt vmcnt(6)
	s_barrier
	s_add_i32 s12, s12, 2
	s_cmp_lt_u32 s12, 14
	s_cbranch_scc1 .Lg1_loop_w3
	ds_read_b128 v[92:95], v84 offset:0
	ds_read_b128 v[100:103], v84 offset:2048
	ds_read_b128 v[148:151], v84 offset:4096
	ds_read_b128 v[180:183], v84 offset:6144
	ds_read_b128 v[188:191], v85 offset:0
	ds_read_b128 v[212:215], v85 offset:2048
	ds_read_b128 v[220:223], v85 offset:4096
	ds_read_b128 v[228:231], v85 offset:6144
	ds_read_b128 v[96:99], v86 offset:0
	ds_read_b128 v[144:147], v86 offset:2048
	ds_read_b128 v[152:155], v86 offset:4096
	ds_read_b128 v[184:187], v86 offset:6144
	ds_read_b128 v[192:195], v87 offset:0
	ds_read_b128 v[216:219], v87 offset:2048
	ds_read_b128 v[224:227], v87 offset:4096
	ds_read_b128 v[252:255], v87 offset:6144
	s_waitcnt lgkmcnt(0)
	s_barrier
	v_mfma_f32_16x16x32_bf16 v[2:5], v[92:95], v[188:191], v[2:5]
	v_mfma_f32_16x16x32_bf16 v[6:9], v[92:95], v[212:215], v[6:9]
	v_mfma_f32_16x16x32_bf16 v[10:13], v[92:95], v[220:223], v[10:13]
	v_mfma_f32_16x16x32_bf16 v[14:17], v[92:95], v[228:231], v[14:17]
	s_mov_b32 m0, s1
	v_mfma_f32_16x16x32_bf16 v[18:21], v[100:103], v[188:191], v[18:21]
	global_load_lds_dwordx4 v[66:67], off
	v_mfma_f32_16x16x32_bf16 v[22:25], v[100:103], v[212:215], v[22:25]
	v_mfma_f32_16x16x32_bf16 v[26:29], v[100:103], v[220:223], v[26:29]
	v_mfma_f32_16x16x32_bf16 v[30:33], v[100:103], v[228:231], v[30:33]
	v_mfma_f32_16x16x32_bf16 v[34:37], v[148:151], v[188:191], v[34:37]
	v_mfma_f32_16x16x32_bf16 v[38:41], v[148:151], v[212:215], v[38:41]
	s_add_i32 m0, s1, 0x400
	v_mfma_f32_16x16x32_bf16 v[42:45], v[148:151], v[220:223], v[42:45]
	global_load_lds_dwordx4 v[70:71], off
	v_mfma_f32_16x16x32_bf16 v[46:49], v[148:151], v[228:231], v[46:49]
	v_mfma_f32_16x16x32_bf16 v[50:53], v[180:183], v[188:191], v[50:53]
	v_mfma_f32_16x16x32_bf16 v[54:57], v[180:183], v[212:215], v[54:57]
	v_mfma_f32_16x16x32_bf16 v[58:61], v[180:183], v[220:223], v[58:61]
	v_mfma_f32_16x16x32_bf16 v[62:65], v[180:183], v[228:231], v[62:65]
	v_mfma_f32_16x16x32_bf16 v[2:5], v[96:99], v[192:195], v[2:5]
	v_mfma_f32_16x16x32_bf16 v[6:9], v[96:99], v[216:219], v[6:9]
	v_mfma_f32_16x16x32_bf16 v[10:13], v[96:99], v[224:227], v[10:13]
	v_mfma_f32_16x16x32_bf16 v[14:17], v[96:99], v[252:255], v[14:17]
	s_add_i32 m0, s1, 0x800
	v_mfma_f32_16x16x32_bf16 v[18:21], v[144:147], v[192:195], v[18:21]
	global_load_lds_dwordx4 v[74:75], off
	v_mfma_f32_16x16x32_bf16 v[22:25], v[144:147], v[216:219], v[22:25]
	v_mfma_f32_16x16x32_bf16 v[26:29], v[144:147], v[224:227], v[26:29]
	v_mfma_f32_16x16x32_bf16 v[30:33], v[144:147], v[252:255], v[30:33]
	v_mfma_f32_16x16x32_bf16 v[34:37], v[152:155], v[192:195], v[34:37]
	v_mfma_f32_16x16x32_bf16 v[38:41], v[152:155], v[216:219], v[38:41]
	s_add_i32 m0, s1, 0xc00
	v_mfma_f32_16x16x32_bf16 v[42:45], v[152:155], v[224:227], v[42:45]
	global_load_lds_dwordx4 v[78:79], off
	v_mfma_f32_16x16x32_bf16 v[46:49], v[152:155], v[252:255], v[46:49]
	v_mfma_f32_16x16x32_bf16 v[50:53], v[184:187], v[192:195], v[50:53]
	v_mfma_f32_16x16x32_bf16 v[54:57], v[184:187], v[216:219], v[54:57]
	v_mfma_f32_16x16x32_bf16 v[58:61], v[184:187], v[224:227], v[58:61]
	v_mfma_f32_16x16x32_bf16 v[62:65], v[184:187], v[252:255], v[62:65]
	s_waitcnt vmcnt(4)
	s_barrier
	ds_read_b128 v[92:95], v84 offset:32768
	ds_read_b128 v[100:103], v84 offset:34816
	ds_read_b128 v[148:151], v84 offset:36864
	ds_read_b128 v[180:183], v84 offset:38912
	ds_read_b128 v[96:99], v86 offset:32768
	ds_read_b128 v[144:147], v86 offset:34816
	ds_read_b128 v[152:155], v86 offset:36864
	ds_read_b128 v[184:187], v86 offset:38912
	s_waitcnt lgkmcnt(0)
	s_barrier
	v_mfma_f32_16x16x32_bf16 v[104:107], v[92:95], v[188:191], v[104:107]
	v_mfma_f32_16x16x32_bf16 v[108:111], v[92:95], v[212:215], v[108:111]
	v_mfma_f32_16x16x32_bf16 v[112:115], v[92:95], v[220:223], v[112:115]
	v_mfma_f32_16x16x32_bf16 v[116:119], v[92:95], v[228:231], v[116:119]
	s_mov_b32 m0, s6
	v_lshl_add_u64 v[82:83], v[66:67], 0, s[26:27]
	v_mfma_f32_16x16x32_bf16 v[128:131], v[100:103], v[188:191], v[128:131]
	global_load_lds_dwordx4 v[82:83], off
	v_lshl_add_u64 v[66:67], v[66:67], 0, s[34:35]
	v_mfma_f32_16x16x32_bf16 v[132:135], v[100:103], v[212:215], v[132:135]
	v_mfma_f32_16x16x32_bf16 v[136:139], v[100:103], v[220:223], v[136:139]
	v_mfma_f32_16x16x32_bf16 v[140:143], v[100:103], v[228:231], v[140:143]
	v_mfma_f32_16x16x32_bf16 v[196:199], v[148:151], v[188:191], v[196:199]
	v_mfma_f32_16x16x32_bf16 v[200:203], v[148:151], v[212:215], v[200:203]
	s_mov_b32 m0, s13
	v_lshl_add_u64 v[82:83], v[70:71], 0, s[26:27]
	v_mfma_f32_16x16x32_bf16 v[204:207], v[148:151], v[220:223], v[204:207]
	global_load_lds_dwordx4 v[82:83], off
	v_lshl_add_u64 v[70:71], v[70:71], 0, s[34:35]
	v_mfma_f32_16x16x32_bf16 v[208:211], v[148:151], v[228:231], v[208:211]
	v_mfma_f32_16x16x32_bf16 v[236:239], v[180:183], v[188:191], v[236:239]
	v_mfma_f32_16x16x32_bf16 v[240:243], v[180:183], v[212:215], v[240:243]
	v_mfma_f32_16x16x32_bf16 v[244:247], v[180:183], v[220:223], v[244:247]
	v_mfma_f32_16x16x32_bf16 v[248:251], v[180:183], v[228:231], v[248:251]
	v_mfma_f32_16x16x32_bf16 v[104:107], v[96:99], v[192:195], v[104:107]
	v_mfma_f32_16x16x32_bf16 v[108:111], v[96:99], v[216:219], v[108:111]
	v_mfma_f32_16x16x32_bf16 v[112:115], v[96:99], v[224:227], v[112:115]
	v_mfma_f32_16x16x32_bf16 v[116:119], v[96:99], v[252:255], v[116:119]
	s_mov_b32 m0, s15
	v_lshl_add_u64 v[82:83], v[74:75], 0, s[26:27]
	v_mfma_f32_16x16x32_bf16 v[128:131], v[144:147], v[192:195], v[128:131]
	global_load_lds_dwordx4 v[82:83], off
	v_lshl_add_u64 v[74:75], v[74:75], 0, s[34:35]
	v_mfma_f32_16x16x32_bf16 v[132:135], v[144:147], v[216:219], v[132:135]
	v_mfma_f32_16x16x32_bf16 v[136:139], v[144:147], v[224:227], v[136:139]
	v_mfma_f32_16x16x32_bf16 v[140:143], v[144:147], v[252:255], v[140:143]
	v_mfma_f32_16x16x32_bf16 v[196:199], v[152:155], v[192:195], v[196:199]
	v_mfma_f32_16x16x32_bf16 v[200:203], v[152:155], v[216:219], v[200:203]
	s_mov_b32 m0, s17
	v_lshl_add_u64 v[82:83], v[78:79], 0, s[26:27]
	v_mfma_f32_16x16x32_bf16 v[204:207], v[152:155], v[224:227], v[204:207]
	global_load_lds_dwordx4 v[82:83], off
	v_lshl_add_u64 v[78:79], v[78:79], 0, s[34:35]
	v_mfma_f32_16x16x32_bf16 v[208:211], v[152:155], v[252:255], v[208:211]
	v_mfma_f32_16x16x32_bf16 v[236:239], v[184:187], v[192:195], v[236:239]
	v_mfma_f32_16x16x32_bf16 v[240:243], v[184:187], v[216:219], v[240:243]
	v_mfma_f32_16x16x32_bf16 v[244:247], v[184:187], v[224:227], v[244:247]
	v_mfma_f32_16x16x32_bf16 v[248:251], v[184:187], v[252:255], v[248:251]
	s_waitcnt vmcnt(4)
	s_barrier
	ds_read_b128 v[92:95], v84 offset:0
	ds_read_b128 v[100:103], v84 offset:2048
	ds_read_b128 v[148:151], v84 offset:4096
	ds_read_b128 v[180:183], v84 offset:6144
	ds_read_b128 v[188:191], v85 offset:32768
	ds_read_b128 v[212:215], v85 offset:34816
	ds_read_b128 v[220:223], v85 offset:36864
	ds_read_b128 v[228:231], v85 offset:38912
	ds_read_b128 v[96:99], v86 offset:0
	ds_read_b128 v[144:147], v86 offset:2048
	ds_read_b128 v[152:155], v86 offset:4096
	ds_read_b128 v[184:187], v86 offset:6144
	ds_read_b128 v[192:195], v87 offset:32768
	ds_read_b128 v[216:219], v87 offset:34816
	ds_read_b128 v[224:227], v87 offset:36864
	ds_read_b128 v[252:255], v87 offset:38912
	s_waitcnt lgkmcnt(0)
	s_barrier
	v_mfma_f32_16x16x32_bf16 v[2:5], v[92:95], v[188:191], v[2:5]
	v_mfma_f32_16x16x32_bf16 v[6:9], v[92:95], v[212:215], v[6:9]
	v_mfma_f32_16x16x32_bf16 v[10:13], v[92:95], v[220:223], v[10:13]
	v_mfma_f32_16x16x32_bf16 v[14:17], v[92:95], v[228:231], v[14:17]
	v_mfma_f32_16x16x32_bf16 v[18:21], v[100:103], v[188:191], v[18:21]
	v_mfma_f32_16x16x32_bf16 v[22:25], v[100:103], v[212:215], v[22:25]
	v_mfma_f32_16x16x32_bf16 v[26:29], v[100:103], v[220:223], v[26:29]
	v_mfma_f32_16x16x32_bf16 v[30:33], v[100:103], v[228:231], v[30:33]
	v_mfma_f32_16x16x32_bf16 v[34:37], v[148:151], v[188:191], v[34:37]
	v_mfma_f32_16x16x32_bf16 v[38:41], v[148:151], v[212:215], v[38:41]
	v_mfma_f32_16x16x32_bf16 v[42:45], v[148:151], v[220:223], v[42:45]
	v_mfma_f32_16x16x32_bf16 v[46:49], v[148:151], v[228:231], v[46:49]
	v_mfma_f32_16x16x32_bf16 v[50:53], v[180:183], v[188:191], v[50:53]
	v_mfma_f32_16x16x32_bf16 v[54:57], v[180:183], v[212:215], v[54:57]
	v_mfma_f32_16x16x32_bf16 v[58:61], v[180:183], v[220:223], v[58:61]
	v_mfma_f32_16x16x32_bf16 v[62:65], v[180:183], v[228:231], v[62:65]
	v_mfma_f32_16x16x32_bf16 v[2:5], v[96:99], v[192:195], v[2:5]
	v_mfma_f32_16x16x32_bf16 v[6:9], v[96:99], v[216:219], v[6:9]
	v_mfma_f32_16x16x32_bf16 v[10:13], v[96:99], v[224:227], v[10:13]
	v_mfma_f32_16x16x32_bf16 v[14:17], v[96:99], v[252:255], v[14:17]
	v_mfma_f32_16x16x32_bf16 v[18:21], v[144:147], v[192:195], v[18:21]
	v_mfma_f32_16x16x32_bf16 v[22:25], v[144:147], v[216:219], v[22:25]
	v_mfma_f32_16x16x32_bf16 v[26:29], v[144:147], v[224:227], v[26:29]
	v_mfma_f32_16x16x32_bf16 v[30:33], v[144:147], v[252:255], v[30:33]
	v_mfma_f32_16x16x32_bf16 v[34:37], v[152:155], v[192:195], v[34:37]
	v_mfma_f32_16x16x32_bf16 v[38:41], v[152:155], v[216:219], v[38:41]
	v_mfma_f32_16x16x32_bf16 v[42:45], v[152:155], v[224:227], v[42:45]
	v_mfma_f32_16x16x32_bf16 v[46:49], v[152:155], v[252:255], v[46:49]
	v_mfma_f32_16x16x32_bf16 v[50:53], v[184:187], v[192:195], v[50:53]
	v_mfma_f32_16x16x32_bf16 v[54:57], v[184:187], v[216:219], v[54:57]
	v_mfma_f32_16x16x32_bf16 v[58:61], v[184:187], v[224:227], v[58:61]
	v_mfma_f32_16x16x32_bf16 v[62:65], v[184:187], v[252:255], v[62:65]
	s_waitcnt vmcnt(0)
	s_barrier
	ds_read_b128 v[92:95], v84 offset:32768
	ds_read_b128 v[100:103], v84 offset:34816
	ds_read_b128 v[148:151], v84 offset:36864
	ds_read_b128 v[180:183], v84 offset:38912
	ds_read_b128 v[96:99], v86 offset:32768
	ds_read_b128 v[144:147], v86 offset:34816
	ds_read_b128 v[152:155], v86 offset:36864
	ds_read_b128 v[184:187], v86 offset:38912
	s_waitcnt lgkmcnt(0)
	s_barrier
	v_mfma_f32_16x16x32_bf16 v[104:107], v[92:95], v[188:191], v[104:107]
	v_mfma_f32_16x16x32_bf16 v[108:111], v[92:95], v[212:215], v[108:111]
	v_mfma_f32_16x16x32_bf16 v[112:115], v[92:95], v[220:223], v[112:115]
	v_mfma_f32_16x16x32_bf16 v[116:119], v[92:95], v[228:231], v[116:119]
	v_mfma_f32_16x16x32_bf16 v[128:131], v[100:103], v[188:191], v[128:131]
	v_mfma_f32_16x16x32_bf16 v[132:135], v[100:103], v[212:215], v[132:135]
	v_mfma_f32_16x16x32_bf16 v[136:139], v[100:103], v[220:223], v[136:139]
	v_mfma_f32_16x16x32_bf16 v[140:143], v[100:103], v[228:231], v[140:143]
	v_mfma_f32_16x16x32_bf16 v[196:199], v[148:151], v[188:191], v[196:199]
	v_mfma_f32_16x16x32_bf16 v[200:203], v[148:151], v[212:215], v[200:203]
	v_mfma_f32_16x16x32_bf16 v[204:207], v[148:151], v[220:223], v[204:207]
	v_mfma_f32_16x16x32_bf16 v[208:211], v[148:151], v[228:231], v[208:211]
	v_mfma_f32_16x16x32_bf16 v[236:239], v[180:183], v[188:191], v[236:239]
	v_mfma_f32_16x16x32_bf16 v[240:243], v[180:183], v[212:215], v[240:243]
	v_mfma_f32_16x16x32_bf16 v[244:247], v[180:183], v[220:223], v[244:247]
	v_mfma_f32_16x16x32_bf16 v[248:251], v[180:183], v[228:231], v[248:251]
	v_mfma_f32_16x16x32_bf16 v[104:107], v[96:99], v[192:195], v[104:107]
	v_mfma_f32_16x16x32_bf16 v[108:111], v[96:99], v[216:219], v[108:111]
	v_mfma_f32_16x16x32_bf16 v[112:115], v[96:99], v[224:227], v[112:115]
	v_mfma_f32_16x16x32_bf16 v[116:119], v[96:99], v[252:255], v[116:119]
	v_mfma_f32_16x16x32_bf16 v[128:131], v[144:147], v[192:195], v[128:131]
	v_mfma_f32_16x16x32_bf16 v[132:135], v[144:147], v[216:219], v[132:135]
	v_mfma_f32_16x16x32_bf16 v[136:139], v[144:147], v[224:227], v[136:139]
	v_mfma_f32_16x16x32_bf16 v[140:143], v[144:147], v[252:255], v[140:143]
	v_mfma_f32_16x16x32_bf16 v[196:199], v[152:155], v[192:195], v[196:199]
	v_mfma_f32_16x16x32_bf16 v[200:203], v[152:155], v[216:219], v[200:203]
	v_mfma_f32_16x16x32_bf16 v[204:207], v[152:155], v[224:227], v[204:207]
	v_mfma_f32_16x16x32_bf16 v[208:211], v[152:155], v[252:255], v[208:211]
	v_mfma_f32_16x16x32_bf16 v[236:239], v[184:187], v[192:195], v[236:239]
	v_mfma_f32_16x16x32_bf16 v[240:243], v[184:187], v[216:219], v[240:243]
	v_mfma_f32_16x16x32_bf16 v[244:247], v[184:187], v[224:227], v[244:247]
	v_mfma_f32_16x16x32_bf16 v[248:251], v[184:187], v[252:255], v[248:251]
	s_waitcnt vmcnt(0) lgkmcnt(0)
	s_barrier
.Lm16_conv:
	s_nop 15
	s_lshr_b32 s72, s1, 12
	s_mulk_i32 s72, 0x4400
	v_and_b32_e32 v88, 63, v156
	v_and_b32_e32 v89, 15, v88
	v_lshrrev_b32_e32 v90, 4, v88
	v_mul_u32_u24_e32 v84, 0x110, v89
	v_lshl_add_u32 v84, v90, 4, v84
	v_add_u32_e32 v84, s72, v84
	v_and_b32_e32 v89, 31, v88
	v_lshrrev_b32_e32 v90, 5, v88
	v_mul_u32_u24_e32 v85, 0x110, v89
	v_lshl_add_u32 v85, v90, 4, v85
	v_add_u32_e32 v85, s72, v85
	ds_write_b128 v84, v[2:5] offset:0
	ds_write_b128 v84, v[6:9] offset:4352
	ds_write_b128 v84, v[10:13] offset:8704
	ds_write_b128 v84, v[14:17] offset:13056
	ds_write_b128 v84, v[18:21] offset:64
	ds_write_b128 v84, v[22:25] offset:4416
	ds_write_b128 v84, v[26:29] offset:8768
	ds_write_b128 v84, v[30:33] offset:13120
	ds_write_b128 v84, v[34:37] offset:128
	ds_write_b128 v84, v[38:41] offset:4480
	ds_write_b128 v84, v[42:45] offset:8832
	ds_write_b128 v84, v[46:49] offset:13184
	ds_write_b128 v84, v[50:53] offset:192
	ds_write_b128 v84, v[54:57] offset:4544
	ds_write_b128 v84, v[58:61] offset:8896
	ds_write_b128 v84, v[62:65] offset:13248
	s_waitcnt lgkmcnt(0)
	ds_read_b128 v[18:21], v85 offset:0
	ds_read_b128 v[22:25], v85 offset:32
	ds_read_b128 v[26:29], v85 offset:64
	ds_read_b128 v[30:33], v85 offset:96
	ds_read_b128 v[50:53], v85 offset:8704
	ds_read_b128 v[54:57], v85 offset:8736
	ds_read_b128 v[58:61], v85 offset:8768
	ds_read_b128 v[62:65], v85 offset:8800
	ds_read_b128 v[2:5], v85 offset:128
	ds_read_b128 v[6:9], v85 offset:160
	ds_read_b128 v[10:13], v85 offset:192
	ds_read_b128 v[14:17], v85 offset:224
	ds_read_b128 v[34:37], v85 offset:8832
	ds_read_b128 v[38:41], v85 offset:8864
	ds_read_b128 v[42:45], v85 offset:8896
	ds_read_b128 v[46:49], v85 offset:8928
	s_waitcnt lgkmcnt(0)
	ds_write_b128 v84, v[104:107] offset:0
	ds_write_b128 v84, v[108:111] offset:4352
	ds_write_b128 v84, v[112:115] offset:8704
	ds_write_b128 v84, v[116:119] offset:13056
	ds_write_b128 v84, v[128:131] offset:64
	ds_write_b128 v84, v[132:135] offset:4416
	ds_write_b128 v84, v[136:139] offset:8768
	ds_write_b128 v84, v[140:143] offset:13120
	ds_write_b128 v84, v[196:199] offset:128
	ds_write_b128 v84, v[200:203] offset:4480
	ds_write_b128 v84, v[204:207] offset:8832
	ds_write_b128 v84, v[208:211] offset:13184
	ds_write_b128 v84, v[236:239] offset:192
	ds_write_b128 v84, v[240:243] offset:4544
	ds_write_b128 v84, v[244:247] offset:8896
	ds_write_b128 v84, v[248:251] offset:13248
	s_waitcnt lgkmcnt(0)
	ds_read_b128 v[104:107], v85 offset:0
	ds_read_b128 v[108:111], v85 offset:32
	ds_read_b128 v[112:115], v85 offset:64
	ds_read_b128 v[116:119], v85 offset:96
	ds_read_b128 v[128:131], v85 offset:8704
	ds_read_b128 v[132:135], v85 offset:8736
	ds_read_b128 v[136:139], v85 offset:8768
	ds_read_b128 v[140:143], v85 offset:8800
	ds_read_b128 v[196:199], v85 offset:128
	ds_read_b128 v[200:203], v85 offset:160
	ds_read_b128 v[204:207], v85 offset:192
	ds_read_b128 v[208:211], v85 offset:224
	ds_read_b128 v[236:239], v85 offset:8832
	ds_read_b128 v[240:243], v85 offset:8864
	ds_read_b128 v[244:247], v85 offset:8896
	ds_read_b128 v[248:251], v85 offset:8928
	s_waitcnt lgkmcnt(0)
	s_barrier
